# scan: serialized ds_read_b128 -> lgkmcnt(0) -> MFMA chains (one temp fragment) software-pipelined 6 deep over free VGPRs v218-v237 with counted lgkmcnt (140 MFMAs in 20 runs)
# speedup vs baseline: 1.0180x; 1.0134x over previous
; __device__ __forceinline__ unsigned cvt_pk(float lo, float hi) { unsigned r; asm volatile("v_cvt_pk_bf16_f32 %0, %1, %2" : "=v"(r) : "v"(lo), "v"(hi)); return r; }
; __device__ __forceinline__ float bflo(unsigned w) { return __uint_as_float(w << 16); }
; __device__ __forceinline__ float bfhi(unsigned w) { return __uint_as_float(w & 0xffff0000u); }
; template <int SPLIT> __device__ __forceinline__ void scan_item(const Params& p, unsigned char* smem, const int item, const int vh) {
;     ...
;             const float m_old = sc[0], M127 = sc[1];
;             const float decay = __expf(m_old - M127);
;             {
;                 const f32x4 a4 = *(const f32x4*)(a_s + sp * 4);
;                 float wsv[4];
; #pragma unroll
;                 for (int i = 0; i < 4; ++i) wsv[i] = __expf(a4[i] - M127);
; #pragma unroll
;                 for (int i = 0; i < 4; ++i) { const u32x4 k = kreg[i]; u32x4 w;
;                     w.x = cvt_pk(bflo(k.x) * wsv[i], bfhi(k.x) * wsv[i]); w.y = cvt_pk(bflo(k.y) * wsv[i], bfhi(k.y) * wsv[i]);
;                     w.z = cvt_pk(bflo(k.z) * wsv[i], bfhi(k.z) * wsv[i]); w.w = cvt_pk(bflo(k.w) * wsv[i], bfhi(k.w) * wsv[i]);
;                     *(u32x4*)(KP + swz(sp * 4 + i, ch)) = w; }
; #pragma unroll
;                 for (int e2 = 0; e2 < 4; ++e2) {
;                     const unsigned k0 = kreg[0][e2], k1 = kreg[1][e2], k2 = kreg[2][e2], k3 = kreg[3][e2];
;                     const unsigned v0 = vreg[0][e2], v1 = vreg[1][e2], v2 = vreg[2][e2], v3 = vreg[3][e2];
;                     const int d0 = ch * 8 + 2 * e2, d1 = d0 + 1; const int co = (sp & 1) * 8;
;                     u32x2 o;
;                     o.x = cvt_pk(bflo(k0) * wsv[0], bflo(k1) * wsv[1]); o.y = cvt_pk(bflo(k2) * wsv[2], bflo(k3) * wsv[3]);
;                     *(u32x2*)(KT + swz(d0, sp >> 1) + co) = o;
;                     o.x = cvt_pk(bfhi(k0) * wsv[0], bfhi(k1) * wsv[1]); o.y = cvt_pk(bfhi(k2) * wsv[2], bfhi(k3) * wsv[3]);
;                     *(u32x2*)(KT + swz(d1, sp >> 1) + co) = o;
;                     o.x = (v0 & 0xffffu) | (v1 << 16); o.y = (v2 & 0xffffu) | (v3 << 16);
;                     *(u32x2*)(VT + swz(d0, sp >> 1) + co) = o;
;                     o.x = (v0 >> 16) | (v1 & 0xffff0000u); o.y = (v2 >> 16) | (v3 & 0xffff0000u);
;                     *(u32x2*)(VT + swz(d1, sp >> 1) + co) = o;
;                 }
;             }
.LBB0_294:
	s_or_b64 exec, exec, s[86:87]
	v_mov_b32_e32 v80, s94
	s_waitcnt lgkmcnt(0)
	s_barrier
	ds_read_b64 v[80:81], v80
	ds_read_b128 v[82:85], v116
	s_waitcnt vmcnt(11)
	v_lshlrev_b32_e32 v86, 16, v44
	v_and_b32_e32 v44, 0xffff0000, v44
	v_lshlrev_b32_e32 v88, 16, v45
	v_and_b32_e32 v45, 0xffff0000, v45
	s_waitcnt lgkmcnt(0)
	v_sub_f32_e32 v82, v82, v81
	v_mul_f32_e32 v82, 0x3fb8aa3b, v82
	v_exp_f32_e32 v82, v82
	v_sub_f32_e32 v83, v83, v81
	v_mul_f32_e32 v83, 0x3fb8aa3b, v83
	v_exp_f32_e32 v83, v83
	v_sub_f32_e32 v84, v84, v81
	v_mul_f32_e32 v84, 0x3fb8aa3b, v84
	v_lshlrev_b32_e32 v90, 16, v46
	v_and_b32_e32 v46, 0xffff0000, v46
	v_exp_f32_e32 v84, v84
	v_sub_f32_e32 v85, v85, v81
	v_mul_f32_e32 v86, v82, v86
	v_mul_f32_e32 v87, v82, v44
	v_cvt_pk_bf16_f32 v44, v86, v87
	v_mul_f32_e32 v88, v82, v88
	v_mul_f32_e32 v89, v82, v45
	v_cvt_pk_bf16_f32 v45, v88, v89
	v_mul_f32_e32 v90, v82, v90
	v_mul_f32_e32 v91, v82, v46
	v_cvt_pk_bf16_f32 v46, v90, v91
	v_lshlrev_b32_e32 v95, 16, v47
	v_and_b32_e32 v47, 0xffff0000, v47
	v_mul_f32_e32 v85, 0x3fb8aa3b, v85
	v_mul_f32_e32 v95, v82, v95
	v_mul_f32_e32 v82, v82, v47
	v_cvt_pk_bf16_f32 v47, v95, v82
	ds_write_b128 v154, v[44:47]
	s_waitcnt vmcnt(10)
	v_lshlrev_b32_e32 v44, 16, v40
	v_and_b32_e32 v40, 0xffff0000, v40
	v_lshlrev_b32_e32 v46, 16, v41
	v_and_b32_e32 v41, 0xffff0000, v41
	v_lshlrev_b32_e32 v112, 16, v42
	v_and_b32_e32 v42, 0xffff0000, v42
	v_exp_f32_e32 v85, v85
	v_mul_f32_e32 v44, v83, v44
	v_mul_f32_e32 v45, v83, v40
	v_cvt_pk_bf16_f32 v40, v44, v45
	v_mul_f32_e32 v46, v83, v46
	v_mul_f32_e32 v47, v83, v41
	v_cvt_pk_bf16_f32 v41, v46, v47
	v_mul_f32_e32 v112, v83, v112
	v_mul_f32_e32 v164, v83, v42
	v_cvt_pk_bf16_f32 v42, v112, v164
	v_lshlrev_b32_e32 v165, 16, v43
	v_and_b32_e32 v43, 0xffff0000, v43
	v_mul_f32_e32 v165, v83, v165
	v_mul_f32_e32 v83, v83, v43
	v_cvt_pk_bf16_f32 v43, v165, v83
	ds_write_b128 v155, v[40:43]
	s_waitcnt vmcnt(9)
	v_lshlrev_b32_e32 v40, 16, v36
	v_and_b32_e32 v36, 0xffff0000, v36
	v_lshlrev_b32_e32 v42, 16, v37
	v_and_b32_e32 v37, 0xffff0000, v37
	v_lshlrev_b32_e32 v166, 16, v38
	v_and_b32_e32 v38, 0xffff0000, v38
	v_mul_f32_e32 v40, v84, v40
	v_mul_f32_e32 v41, v84, v36
	v_cvt_pk_bf16_f32 v36, v40, v41
	v_mul_f32_e32 v42, v84, v42
	v_mul_f32_e32 v43, v84, v37
	v_cvt_pk_bf16_f32 v37, v42, v43
	v_mul_f32_e32 v166, v84, v166
	v_mul_f32_e32 v167, v84, v38
	v_cvt_pk_bf16_f32 v38, v166, v167
	v_lshlrev_b32_e32 v168, 16, v39
	v_and_b32_e32 v39, 0xffff0000, v39
	v_mul_f32_e32 v168, v84, v168
	v_mul_f32_e32 v84, v84, v39
	v_cvt_pk_bf16_f32 v39, v168, v84
	ds_write_b128 v156, v[36:39]
	s_waitcnt vmcnt(7)
	v_lshlrev_b32_e32 v36, 16, v32
	v_and_b32_e32 v32, 0xffff0000, v32
	v_lshlrev_b32_e32 v38, 16, v33
	v_and_b32_e32 v33, 0xffff0000, v33
	v_lshlrev_b32_e32 v169, 16, v34
	v_and_b32_e32 v34, 0xffff0000, v34
	v_mul_f32_e32 v36, v85, v36
	v_mul_f32_e32 v37, v85, v32
	v_cvt_pk_bf16_f32 v32, v36, v37
	v_mul_f32_e32 v38, v85, v38
	v_mul_f32_e32 v39, v85, v33
	v_cvt_pk_bf16_f32 v33, v38, v39
	v_mul_f32_e32 v169, v85, v169
	v_mul_f32_e32 v171, v85, v34
	v_cvt_pk_bf16_f32 v34, v169, v171
	v_lshlrev_b32_e32 v172, 16, v35
	v_and_b32_e32 v35, 0xffff0000, v35
	v_mul_f32_e32 v172, v85, v172
	v_mul_f32_e32 v85, v85, v35
	v_cvt_pk_bf16_f32 v35, v172, v85
	ds_write_b128 v157, v[32:35]
	v_cvt_pk_bf16_f32 v32, v86, v44
	v_cvt_pk_bf16_f32 v33, v40, v36
	v_add_u32_e32 v34, v120, v136
	ds_write_b64 v34, v[32:33]
	v_cvt_pk_bf16_f32 v32, v87, v45
	v_cvt_pk_bf16_f32 v33, v41, v37
	v_add_u32_e32 v34, v120, v137
	ds_write_b64 v34, v[32:33]
	s_waitcnt vmcnt(4)
	v_lshlrev_b32_e32 v32, 16, v4
	v_lshlrev_b32_e32 v33, 16, v16
	v_and_or_b32 v32, v0, s91, v32
	v_and_or_b32 v33, v8, s91, v33
	v_add_u32_e32 v34, v121, v136
	v_lshrrev_b32_e32 v0, 16, v0
	ds_write_b64 v34, v[32:33] offset:32768
	v_and_or_b32 v32, v4, s90, v0
	v_lshrrev_b32_e32 v0, 16, v8
	v_and_or_b32 v33, v16, s90, v0
	v_add_u32_e32 v0, v121, v137
	ds_write_b64 v0, v[32:33] offset:32768
	v_add_u32_e32 v0, v120, v138
	v_cvt_pk_bf16_f32 v32, v88, v46
	v_cvt_pk_bf16_f32 v33, v42, v38
	ds_write_b64 v0, v[32:33]
	v_add_u32_e32 v0, v120, v139
	v_cvt_pk_bf16_f32 v32, v89, v47
	v_cvt_pk_bf16_f32 v33, v43, v39
	ds_write_b64 v0, v[32:33]
	v_lshlrev_b32_e32 v0, 16, v5
	v_and_or_b32 v32, v1, s91, v0
	v_lshlrev_b32_e32 v0, 16, v17
	v_and_or_b32 v33, v9, s91, v0
	v_add_u32_e32 v0, v121, v138
	ds_write_b64 v0, v[32:33] offset:32768
	v_lshrrev_b32_e32 v0, 16, v1
	v_lshrrev_b32_e32 v1, 16, v9
	v_and_or_b32 v0, v5, s90, v0
	v_and_or_b32 v1, v17, s90, v1
	v_add_u32_e32 v4, v121, v139
	ds_write_b64 v4, v[0:1] offset:32768
	v_cvt_pk_bf16_f32 v0, v90, v112
	v_cvt_pk_bf16_f32 v1, v166, v169
	v_add_u32_e32 v4, v120, v140
	ds_write_b64 v4, v[0:1]
	v_cvt_pk_bf16_f32 v0, v91, v164
	v_cvt_pk_bf16_f32 v1, v167, v171
	v_add_u32_e32 v4, v120, v141
	ds_write_b64 v4, v[0:1]
	v_lshlrev_b32_e32 v0, 16, v6
	v_lshlrev_b32_e32 v1, 16, v18
	v_and_or_b32 v0, v2, s91, v0
	v_and_or_b32 v1, v10, s91, v1
	v_add_u32_e32 v4, v121, v140
	ds_write_b64 v4, v[0:1] offset:32768
	v_lshrrev_b32_e32 v0, 16, v2
	v_lshrrev_b32_e32 v1, 16, v10
	v_and_or_b32 v0, v6, s90, v0
	v_and_or_b32 v1, v18, s90, v1
	v_add_u32_e32 v2, v121, v141
	ds_write_b64 v2, v[0:1] offset:32768
	v_cvt_pk_bf16_f32 v0, v95, v165
	v_cvt_pk_bf16_f32 v1, v168, v172
	v_add_u32_e32 v2, v120, v142
	ds_write_b64 v2, v[0:1]
	v_cvt_pk_bf16_f32 v0, v82, v83
	v_cvt_pk_bf16_f32 v1, v84, v85
	v_add_u32_e32 v2, v120, v143
	ds_write_b64 v2, v[0:1]
	v_lshlrev_b32_e32 v0, 16, v7
	v_lshlrev_b32_e32 v1, 16, v19
	v_and_or_b32 v0, v3, s91, v0
	v_and_or_b32 v1, v11, s91, v1
	v_add_u32_e32 v2, v121, v142
	ds_write_b64 v2, v[0:1] offset:32768
	v_lshrrev_b32_e32 v0, 16, v3
	v_lshrrev_b32_e32 v1, 16, v11
	v_and_or_b32 v0, v7, s90, v0
	v_and_or_b32 v1, v19, s90, v1
	v_add_u32_e32 v2, v121, v143
	s_lshl_b32 s0, vcc_lo, 7
	ds_write_b64 v2, v[0:1] offset:32768
	v_or_b32_e32 v0, s0, v113
	v_mul_lo_u32 v0, v0, s3
	v_add_u32_e32 v4, s33, v0
	v_ashrrev_i32_e32 v5, 31, v4
	v_lshlrev_b64 v[0:1], 10, v[4:5]
	v_add_u32_e32 v8, s3, v4
	v_lshl_add_u64 v[0:1], v[92:93], 0, v[0:1]
	v_ashrrev_i32_e32 v9, 31, v8
	s_waitcnt lgkmcnt(0)
	s_barrier
; #define SCAN_LOAD(j) do { \
;         _Pragma("unroll") for (int i = 0; i < 4; ++i) { const size_t r = (size_t)(rfirst + rstep * ((j) * 128 + sp * 4 + i)); \
;             kreg[i] = *(const u32x4*)(K0 + r * 512 + h * 128 + ch * 8); vreg[i] = *(const u32x4*)(P0 + r * LDP + 1536 + h * 128 + ch * 8); } \
;         } while (0)
; template <int SPLIT> __device__ __forceinline__ void scan_item(const Params& p, unsigned char* smem, const int item, const int vh) {
;     ...
;             SCAN_LOAD(jn);
;             __builtin_amdgcn_sched_barrier(0);
;             const int l = wid * 16 + li;
;             const float Ml = M_s[l], gl = g_s[l];
;             f32x4 acc[8];
; #pragma unroll
;             for (int nb = 0; nb < 8; ++nb) acc[nb] = (f32x4){0.f, 0.f, 0.f, 0.f};
;             mm16<8>(acc, KP, qf, lane);
	global_load_dwordx4 v[44:47], v[0:1], off
	v_mad_i64_i32 v[0:1], s[4:5], v4, s88, v[108:109]
	v_lshlrev_b64 v[4:5], 10, v[8:9]
	v_add_u32_e32 v16, s3, v8
	v_lshl_add_u64 v[4:5], v[92:93], 0, v[4:5]
	v_ashrrev_i32_e32 v17, 31, v16
	global_load_dwordx4 v[40:43], v[4:5], off
	v_mad_i64_i32 v[4:5], s[4:5], v8, s88, v[108:109]
	v_lshlrev_b64 v[8:9], 10, v[16:17]
	v_lshl_add_u64 v[8:9], v[92:93], 0, v[8:9]
	global_load_dwordx4 v[36:39], v[8:9], off
	v_mad_i64_i32 v[8:9], s[4:5], v16, s88, v[108:109]
	v_add_u32_e32 v16, s3, v16
	v_ashrrev_i32_e32 v17, 31, v16
	v_lshlrev_b64 v[18:19], 10, v[16:17]
	v_lshl_add_u64 v[18:19], v[92:93], 0, v[18:19]
	v_mad_i64_i32 v[16:17], s[4:5], v16, s88, v[108:109]
	global_load_dwordx4 v[0:3], v[0:1], off offset:3072
	v_sub_f32_e32 v81, v80, v81
	global_load_dwordx4 v[4:7], v[4:5], off offset:3072
	v_mul_f32_e32 v81, 0x3fb8aa3b, v81
	global_load_dwordx4 v[8:11], v[8:9], off offset:3072
	v_exp_f32_e32 v112, v81
	global_load_dwordx4 v[32:35], v[18:19], off
	s_nop 0
	global_load_dwordx4 v[16:19], v[16:17], off offset:3072
	v_add_u32_e32 v81, 0, v125
	ds_read_b128 v[82:85], v81
	ds_read_b128 v[86:89], v81 offset:4096
	ds_read_b32 v171, v123
	ds_read_b128 v[164:167], v81 offset:8192
	ds_read_b128 v[172:175], v81 offset:12288
	ds_read_b32 v177, v122
	s_waitcnt vmcnt(11) lgkmcnt(5)
	v_mfma_f32_16x16x32_bf16 v[82:85], v[82:85], v[28:31], 0
	s_waitcnt lgkmcnt(4)
	v_mfma_f32_16x16x32_bf16 v[86:89], v[86:89], v[28:31], 0
	s_waitcnt lgkmcnt(2)
	v_mfma_f32_16x16x32_bf16 v[166:169], v[164:167], v[28:31], 0
	s_waitcnt lgkmcnt(1)
	v_mfma_f32_16x16x32_bf16 v[172:175], v[172:175], v[28:31], 0
	ds_read_b128 v[178:181], v81 offset:16384
	ds_read_b128 v[182:185], v81 offset:20480
	ds_read_b128 v[186:189], v81 offset:24576
	ds_read_b128 v[190:193], v81 offset:28672
	s_waitcnt lgkmcnt(3)
	v_mfma_f32_16x16x32_bf16 v[178:181], v[178:181], v[28:31], 0
	s_waitcnt lgkmcnt(2)
	v_mfma_f32_16x16x32_bf16 v[182:185], v[182:185], v[28:31], 0
	s_waitcnt lgkmcnt(1)
	v_mfma_f32_16x16x32_bf16 v[186:189], v[186:189], v[28:31], 0
	s_waitcnt lgkmcnt(0)
	v_mfma_f32_16x16x32_bf16 v[190:193], v[190:193], v[28:31], 0
	v_add_u32_e32 v165, 0, v127
	ds_read_b128 v[194:197], v165
	s_waitcnt vmcnt(10) lgkmcnt(0)
	v_mfma_f32_16x16x32_bf16 v[82:85], v[194:197], v[24:27], v[82:85]
	ds_read_b128 v[194:197], v165 offset:4096
	s_waitcnt lgkmcnt(0)
	v_mfma_f32_16x16x32_bf16 v[86:89], v[194:197], v[24:27], v[86:89]
	ds_read_b128 v[194:197], v165 offset:8192
	s_waitcnt lgkmcnt(0)
	v_mfma_f32_16x16x32_bf16 v[194:197], v[194:197], v[24:27], v[166:169]
	s_nop 2
	ds_read_b128 v[222:225], v165 offset:12288
	ds_read_b128 v[226:229], v165 offset:16384
	ds_read_b128 v[230:233], v165 offset:20480
	ds_read_b128 v[234:237], v165 offset:24576
	ds_read_b128 v[166:169], v165 offset:28672
	s_waitcnt lgkmcnt(4)
	v_mfma_f32_16x16x32_bf16 v[172:175], v[222:225], v[24:27], v[172:175]
	s_nop 0
	s_waitcnt lgkmcnt(3)
	v_mfma_f32_16x16x32_bf16 v[178:181], v[226:229], v[24:27], v[178:181]
	s_nop 0
	s_waitcnt lgkmcnt(2)
	v_mfma_f32_16x16x32_bf16 v[182:185], v[230:233], v[24:27], v[182:185]
	s_nop 0
	s_waitcnt lgkmcnt(1)
	v_mfma_f32_16x16x32_bf16 v[186:189], v[234:237], v[24:27], v[186:189]
	s_nop 0
	s_waitcnt lgkmcnt(0)
	v_mfma_f32_16x16x32_bf16 v[190:193], v[166:169], v[24:27], v[190:193]
	s_nop 0
	v_add_u32_e32 v166, 0, v129
	ds_read_b128 v[226:229], v166
	ds_read_b128 v[230:233], v166 offset:4096
	ds_read_b128 v[234:237], v166 offset:8192
	ds_read_b128 v[198:201], v166 offset:12288
	ds_read_b128 v[218:221], v166 offset:16384
	ds_read_b128 v[222:225], v166 offset:20480
	s_waitcnt vmcnt(9) lgkmcnt(5)
	v_mfma_f32_16x16x32_bf16 v[82:85], v[226:229], v[20:23], v[82:85]
	ds_read_b128 v[226:229], v166 offset:24576
	s_waitcnt lgkmcnt(5)
	v_mfma_f32_16x16x32_bf16 v[86:89], v[230:233], v[20:23], v[86:89]
	ds_read_b128 v[230:233], v166 offset:28672
	s_waitcnt lgkmcnt(5)
	v_mfma_f32_16x16x32_bf16 v[194:197], v[234:237], v[20:23], v[194:197]
	v_add_u32_e32 v167, 0, v131
	ds_read_b128 v[234:237], v167
	s_waitcnt lgkmcnt(5)
	v_mfma_f32_16x16x32_bf16 v[172:175], v[198:201], v[20:23], v[172:175]
	ds_read_b128 v[198:201], v167 offset:4096
	s_waitcnt lgkmcnt(5)
	v_mfma_f32_16x16x32_bf16 v[178:181], v[218:221], v[20:23], v[178:181]
	ds_read_b128 v[218:221], v167 offset:8192
	s_waitcnt lgkmcnt(5)
	v_mfma_f32_16x16x32_bf16 v[182:185], v[222:225], v[20:23], v[182:185]
	ds_read_b128 v[222:225], v167 offset:12288
	s_waitcnt lgkmcnt(5)
	v_mfma_f32_16x16x32_bf16 v[186:189], v[226:229], v[20:23], v[186:189]
	ds_read_b128 v[226:229], v167 offset:16384
	s_waitcnt lgkmcnt(5)
	v_mfma_f32_16x16x32_bf16 v[190:193], v[230:233], v[20:23], v[190:193]
	ds_read_b128 v[230:233], v167 offset:20480
	s_waitcnt vmcnt(8) lgkmcnt(5)
	v_mfma_f32_16x16x32_bf16 v[82:85], v[234:237], v[12:15], v[82:85]
	ds_read_b128 v[234:237], v167 offset:24576
	s_waitcnt lgkmcnt(5)
	v_mfma_f32_16x16x32_bf16 v[86:89], v[198:201], v[12:15], v[86:89]
	ds_read_b128 v[198:201], v167 offset:28672
	s_waitcnt lgkmcnt(5)
	v_mfma_f32_16x16x32_bf16 v[194:197], v[218:221], v[12:15], v[194:197]
	s_nop 0
	s_waitcnt lgkmcnt(4)
	v_mfma_f32_16x16x32_bf16 v[172:175], v[222:225], v[12:15], v[172:175]
	s_nop 0
	s_waitcnt lgkmcnt(3)
	v_mfma_f32_16x16x32_bf16 v[178:181], v[226:229], v[12:15], v[178:181]
	s_nop 0
	s_waitcnt lgkmcnt(2)
	v_mfma_f32_16x16x32_bf16 v[182:185], v[230:233], v[12:15], v[182:185]
	s_nop 0
	s_waitcnt lgkmcnt(1)
	v_mfma_f32_16x16x32_bf16 v[186:189], v[234:237], v[12:15], v[186:189]
	s_nop 0
	s_waitcnt lgkmcnt(0)
	v_mfma_f32_16x16x32_bf16 v[190:193], v[198:201], v[12:15], v[190:193]
	s_nop 0
	v_mov_b32_e32 v90, s6
	ds_read_b32 v90, v90
	s_waitcnt lgkmcnt(0)
; __device__ __forceinline__ unsigned cvt_pk(float lo, float hi) { unsigned r; asm volatile("v_cvt_pk_bf16_f32 %0, %1, %2" : "=v"(r) : "v"(lo), "v"(hi)); return r; }
; __device__ __forceinline__ float bflo(unsigned w) { return __uint_as_float(w << 16); }
; __device__ __forceinline__ float bfhi(unsigned w) { return __uint_as_float(w & 0xffff0000u); }
; template <int SPLIT> __device__ __forceinline__ void scan_item(const Params& p, unsigned char* smem, const int item, const int vh) {
;     ...
;             const float rowf = __expf(fminf(sc[1] - Ml, 80.f));
; #pragma unroll
;             for (int nb = 0; nb < 8; ++nb) { float pv[4];
; #pragma unroll
;                 for (int jj = 0; jj < 4; ++jj) { const int s = nb * 16 + kq * 4 + jj; pv[jj] = (s <= l) ? acc[nb][jj] * rowf : 0.f; rs += pv[jj]; }
;                 pp[nb].x = cvt_pk(pv[0], pv[1]); pp[nb].y = cvt_pk(pv[2], pv[3]); }
;             __builtin_amdgcn_sched_barrier(0);
;             float nq = 0.f;
; #pragma unroll
;             for (int ks = 0; ks < 4; ++ks) { const f32x4 n0 = *(const f32x4*)(n_s + ks * 32 + kq * 8), n1 = *(const f32x4*)(n_s + ks * 32 + kq * 8 + 4);
;                 const u32x4 qw = *(const u32x4*)&qf[ks];
;                 nq += bflo(qw.x) * n0[0] + bfhi(qw.x) * n0[1] + bflo(qw.y) * n0[2] + bfhi(qw.y) * n0[3] + bflo(qw.z) * n1[0] + bfhi(qw.z) * n1[1] + bflo(qw.w) * n1[2] + bfhi(qw.w) * n1[3]; }
	v_sub_f32_e32 v90, v90, v177
	v_min_f32_e32 v90, 0x42a00000, v90
	v_mul_f32_e32 v90, 0x3fb8aa3b, v90
	v_exp_f32_e32 v164, v90
	s_nop 0
	v_mul_f32_e32 v82, v82, v164
	v_mul_f32_e32 v83, v83, v164
	v_cndmask_b32_e64 v82, v82, 0, s[10:11]
	v_mul_f32_e32 v84, v84, v164
	v_cndmask_b32_e64 v83, 0, v83, s[12:13]
	v_add_f32_e32 v90, 0, v82
	v_mul_f32_e32 v85, v85, v164
	v_cndmask_b32_e64 v84, v84, 0, s[14:15]
	v_cvt_pk_bf16_f32 v82, v82, v83
	v_add_f32_e32 v83, v83, v90
	v_cndmask_b32_e64 v85, v85, 0, s[16:17]
	v_add_f32_e32 v83, v84, v83
	v_add_f32_e32 v90, v85, v83
	v_cvt_pk_bf16_f32 v83, v84, v85
	v_mul_f32_e32 v84, v86, v164
	v_cndmask_b32_e64 v84, v84, 0, s[18:19]
	v_mul_f32_e32 v86, v87, v164
	v_add_f32_e32 v85, v84, v90
	v_cndmask_b32_e64 v86, v86, 0, s[20:21]
	v_mul_f32_e32 v87, v88, v164
	v_add_f32_e32 v85, v86, v85
	v_cndmask_b32_e64 v87, v87, 0, s[22:23]
	v_mul_f32_e32 v88, v89, v164
	v_add_f32_e32 v85, v87, v85
	v_cndmask_b32_e64 v88, v88, 0, s[24:25]
	v_cvt_pk_bf16_f32 v84, v84, v86
	v_mul_f32_e32 v86, v194, v164
	v_add_f32_e32 v89, v88, v85
	v_cvt_pk_bf16_f32 v85, v87, v88
	v_cndmask_b32_e64 v86, v86, 0, s[26:27]
	v_mul_f32_e32 v88, v195, v164
	v_add_f32_e32 v87, v86, v89
	v_cndmask_b32_e64 v88, v88, 0, s[28:29]
	v_mul_f32_e32 v89, v196, v164
	v_add_f32_e32 v87, v88, v87
	v_cndmask_b32_e64 v89, v89, 0, s[30:31]
	v_mul_f32_e32 v90, v197, v164
	v_add_f32_e32 v87, v89, v87
	v_cndmask_b32_e64 v90, v90, 0, s[34:35]
	v_cvt_pk_bf16_f32 v86, v86, v88
	v_mul_f32_e32 v88, v172, v164
	v_add_f32_e32 v91, v90, v87
	v_cvt_pk_bf16_f32 v87, v89, v90
	v_cndmask_b32_e64 v88, v88, 0, s[36:37]
	v_mul_f32_e32 v90, v173, v164
	v_add_f32_e32 v89, v88, v91
	v_cndmask_b32_e64 v90, v90, 0, s[38:39]
	v_mul_f32_e32 v91, v174, v164
	v_add_f32_e32 v89, v90, v89
	v_cndmask_b32_e64 v91, v91, 0, s[40:41]
	v_mul_f32_e32 v95, v175, v164
	v_add_f32_e32 v89, v91, v89
	v_cndmask_b32_e64 v95, v95, 0, s[42:43]
	v_cvt_pk_bf16_f32 v88, v88, v90
	v_mul_f32_e32 v90, v178, v164
	v_add_f32_e32 v168, v95, v89
	v_cvt_pk_bf16_f32 v89, v91, v95
	v_cndmask_b32_e64 v90, v90, 0, s[44:45]
	v_mul_f32_e32 v95, v179, v164
	v_add_f32_e32 v91, v90, v168
	v_cndmask_b32_e64 v95, v95, 0, s[46:47]
	v_mul_f32_e32 v168, v180, v164
	v_add_f32_e32 v91, v95, v91
	v_cndmask_b32_e64 v168, v168, 0, s[48:49]
	v_mul_f32_e32 v169, v181, v164
	v_add_f32_e32 v91, v168, v91
	v_cndmask_b32_e64 v169, v169, 0, s[50:51]
	v_cvt_pk_bf16_f32 v90, v90, v95
	v_mul_f32_e32 v95, v182, v164
	v_add_f32_e32 v172, v169, v91
	v_cvt_pk_bf16_f32 v91, v168, v169
	v_cndmask_b32_e64 v95, v95, 0, s[52:53]
	v_mul_f32_e32 v168, v183, v164
	v_add_f32_e32 v169, v95, v172
	v_cndmask_b32_e64 v183, v168, 0, s[54:55]
	v_cvt_pk_bf16_f32 v198, v95, v183
	v_mul_f32_e32 v95, v186, v164
	v_mul_f32_e32 v168, v184, v164
	v_cndmask_b32_e64 v201, v95, 0, s[60:61]
	v_mul_f32_e32 v95, v187, v164
	v_cndmask_b32_e64 v195, v168, 0, s[56:57]
	v_mul_f32_e32 v168, v185, v164
	v_cndmask_b32_e64 v203, v95, 0, s[62:63]
	v_mul_f32_e32 v95, v188, v164
	v_cndmask_b32_e64 v197, v168, 0, s[58:59]
	v_cndmask_b32_e64 v205, v95, 0, s[64:65]
	v_mul_f32_e32 v95, v189, v164
	v_mul_f32_e32 v168, v191, v164
	v_cndmask_b32_e64 v207, v95, 0, s[66:67]
	v_mul_f32_e32 v95, v190, v164
	v_cndmask_b32_e64 v214, v168, 0, s[70:71]
	v_mul_f32_e32 v168, v192, v164
	v_mul_f32_e32 v164, v193, v164
	v_cvt_pk_bf16_f32 v199, v195, v197
	v_cvt_pk_bf16_f32 v208, v201, v203
	v_cvt_pk_bf16_f32 v209, v205, v207
	v_cndmask_b32_e64 v95, v95, 0, s[68:69]
	v_cndmask_b32_e64 v215, v168, 0, s[72:73]
	v_cndmask_b32_e64 v216, v164, 0, s[74:75]
	v_cvt_pk_bf16_f32 v190, v95, v214
	v_cvt_pk_bf16_f32 v191, v215, v216
	ds_read_b128 v[172:175], v158
	ds_read_b128 v[178:181], v158 offset:16
	v_lshlrev_b32_e32 v164, 16, v28
	v_and_b32_e32 v168, 0xffff0000, v28
	v_and_b32_e32 v187, 0xffff0000, v20
	s_waitcnt lgkmcnt(1)
	v_mul_f32_e32 v182, v172, v164
	v_lshlrev_b32_e32 v164, 16, v29
	v_mul_f32_e32 v194, v174, v164
	v_and_b32_e32 v164, 0xffff0000, v29
	v_mul_f32_e32 v168, v173, v168
	v_mul_f32_e32 v196, v175, v164
	v_lshlrev_b32_e32 v164, 16, v30
	ds_read_b128 v[172:175], v158 offset:128
	s_waitcnt lgkmcnt(1)
	v_mul_f32_e32 v200, v178, v164
	v_and_b32_e32 v164, 0xffff0000, v30
	v_mul_f32_e32 v202, v179, v164
	v_lshlrev_b32_e32 v164, 16, v31
	v_mul_f32_e32 v204, v180, v164
	v_and_b32_e32 v164, 0xffff0000, v31
	v_pk_add_f32 v[168:169], v[182:183], v[168:169]
	v_mul_f32_e32 v206, v181, v164
	ds_read_b128 v[178:181], v158 offset:144
	v_and_b32_e32 v183, 0xffff0000, v24
	v_lshlrev_b32_e32 v182, 16, v24
	s_waitcnt lgkmcnt(1)
	v_mul_f32_e32 v164, v173, v183
	v_pk_fma_f32 v[172:173], v[172:173], v[182:183], v[164:165] op_sel_hi:[1,1,0]
	v_and_b32_e32 v183, 0xffff0000, v25
	v_lshlrev_b32_e32 v182, 16, v25
	v_pk_fma_f32 v[172:173], v[174:175], v[182:183], v[172:173]
	v_mul_f32_e32 v164, v175, v183
	v_pk_add_f32 v[172:173], v[164:165], v[172:173] op_sel_hi:[0,1]
	v_and_b32_e32 v175, 0xffff0000, v26
	v_lshlrev_b32_e32 v174, 16, v26
	s_waitcnt lgkmcnt(0)
	v_pk_fma_f32 v[172:173], v[178:179], v[174:175], v[172:173]
	v_mul_f32_e32 v164, v179, v175
	v_pk_add_f32 v[178:179], v[164:165], v[172:173] op_sel_hi:[0,1]
	ds_read_b128 v[172:175], v158 offset:256
	ds_read_b128 v[182:185], v158 offset:272
	v_lshlrev_b32_e32 v186, 16, v20
	v_and_b32_e32 v213, 0xffff0000, v12
	v_lshlrev_b32_e32 v212, 16, v12
	s_waitcnt lgkmcnt(1)
	v_mul_f32_e32 v164, v173, v187
	v_pk_fma_f32 v[172:173], v[172:173], v[186:187], v[164:165] op_sel_hi:[1,1,0]
	v_and_b32_e32 v187, 0xffff0000, v21
	v_lshlrev_b32_e32 v186, 16, v21
	v_pk_fma_f32 v[172:173], v[174:175], v[186:187], v[172:173]
	v_mul_f32_e32 v164, v175, v187
	v_pk_add_f32 v[172:173], v[164:165], v[172:173] op_sel_hi:[0,1]
	v_and_b32_e32 v175, 0xffff0000, v22
	v_lshlrev_b32_e32 v174, 16, v22
	s_waitcnt lgkmcnt(0)
; template <int SPLIT> __device__ __forceinline__ void scan_item(const Params& p, unsigned char* smem, const int item, const int vh) {
;     ...
;             rs += __shfl_xor(rs, 16); rs += __shfl_xor(rs, 32); nq += __shfl_xor(nq, 16); nq += __shfl_xor(nq, 32);
;             const float exl = __expf(m_old - Ml);
;             const float den = rs + exl * nq;
;             const float hinv = __builtin_amdgcn_rcpf(fmaxf(fabsf(den), __expf(-(gl + Ml))));
;             __syncthreads();
; #pragma unroll
;             for (int nb = 0; nb < 8; ++nb) *(u32x2*)(KP + swz(l, nb * 2 + (kq >> 1)) + (kq & 1) * 8) = pp[nb];
;             f32x4 acc2[NBV];
; #pragma unroll
;             for (int nb = 0; nb < NBV; ++nb) acc2[nb] = (f32x4){0.f, 0.f, 0.f, 0.f};
;             __builtin_amdgcn_sched_barrier(0);
;             mm16<NBV>(acc2, CS + vh * 16384, qf, lane);
	v_pk_fma_f32 v[172:173], v[182:183], v[174:175], v[172:173]
	v_mul_f32_e32 v164, v183, v175
	v_pk_add_f32 v[182:183], v[164:165], v[172:173] op_sel_hi:[0,1]
	ds_read_b128 v[172:175], v158 offset:384
	ds_read_b128 v[186:189], v158 offset:400
	v_pk_add_f32 v[168:169], v[194:195], v[168:169]
	v_and_b32_e32 v193, 0xffff0000, v27
	v_pk_add_f32 v[168:169], v[196:197], v[168:169]
	s_waitcnt lgkmcnt(1)
	v_mul_f32_e32 v164, v173, v213
	v_pk_fma_f32 v[172:173], v[172:173], v[212:213], v[164:165] op_sel_hi:[1,1,0]
	v_and_b32_e32 v213, 0xffff0000, v13
	v_lshlrev_b32_e32 v212, 16, v13
	v_pk_fma_f32 v[172:173], v[174:175], v[212:213], v[172:173]
	v_mul_f32_e32 v164, v175, v213
	v_pk_add_f32 v[172:173], v[164:165], v[172:173] op_sel_hi:[0,1]
	v_and_b32_e32 v175, 0xffff0000, v14
	v_lshlrev_b32_e32 v174, 16, v14
	s_waitcnt lgkmcnt(0)
	v_pk_fma_f32 v[172:173], v[186:187], v[174:175], v[172:173]
	v_mul_f32_e32 v164, v187, v175
	v_pk_add_f32 v[172:173], v[164:165], v[172:173] op_sel_hi:[0,1]
	v_and_b32_e32 v175, 0xffff0000, v15
	v_lshlrev_b32_e32 v174, 16, v15
	v_pk_add_f32 v[168:169], v[200:201], v[168:169]
	v_lshlrev_b32_e32 v192, 16, v27
	v_pk_fma_f32 v[172:173], v[188:189], v[174:175], v[172:173]
	v_and_b32_e32 v174, 64, v163
	v_pk_add_f32 v[168:169], v[202:203], v[168:169]
	v_pk_fma_f32 v[178:179], v[180:181], v[192:193], v[178:179]
	v_add_u32_e32 v180, 64, v174
	v_pk_add_f32 v[168:169], v[204:205], v[168:169]
	v_mul_f32_e32 v174, v181, v193
	v_and_b32_e32 v211, 0xffff0000, v23
	v_lshlrev_b32_e32 v210, 16, v23
	v_pk_add_f32 v[168:169], v[206:207], v[168:169]
	v_pk_add_f32 v[178:179], v[174:175], v[178:179] op_sel_hi:[0,1]
	v_pk_fma_f32 v[182:183], v[184:185], v[210:211], v[182:183]
	v_pk_add_f32 v[168:169], v[94:95], v[168:169]
	v_mov_b32_e32 v179, v214
	v_mul_f32_e32 v174, v185, v211
	v_xor_b32_e32 v164, 16, v163
	v_pk_add_f32 v[168:169], v[178:179], v[168:169]
	v_pk_add_f32 v[178:179], v[174:175], v[182:183] op_sel_hi:[0,1]
	v_mul_f32_e32 v174, v189, v175
	v_cmp_lt_i32_e32 vcc, v164, v180
	v_mov_b32_e32 v179, v215
	v_pk_add_f32 v[172:173], v[174:175], v[172:173] op_sel_hi:[0,1]
	v_cndmask_b32_e32 v164, v163, v164, vcc
	v_pk_add_f32 v[168:169], v[178:179], v[168:169]
	v_mov_b32_e32 v173, v216
	v_lshlrev_b32_e32 v164, 2, v164
	v_pk_add_f32 v[168:169], v[172:173], v[168:169]
	ds_bpermute_b32 v173, v164, v169
	ds_bpermute_b32 v172, v164, v168
	v_xor_b32_e32 v95, 32, v163
	v_cmp_lt_i32_e32 vcc, v95, v180
	v_sub_f32_e32 v80, v80, v177
	v_mul_f32_e32 v80, 0x3fb8aa3b, v80
	v_cndmask_b32_e32 v95, v163, v95, vcc
	v_lshlrev_b32_e32 v95, 2, v95
	s_waitcnt lgkmcnt(0)
	v_pk_add_f32 v[168:169], v[168:169], v[172:173]
	ds_bpermute_b32 v173, v95, v169
	ds_bpermute_b32 v172, v95, v168
	v_add_f32_e32 v171, v177, v171
	v_exp_f32_e32 v80, v80
	v_mul_f32_e32 v171, 0xbfb8aa3b, v171
	v_exp_f32_e32 v171, v171
	s_waitcnt lgkmcnt(0)
	v_pk_add_f32 v[168:169], v[168:169], v[172:173]
	s_nop 0
	v_fmac_f32_e32 v169, v80, v168
	v_max_f32_e64 v168, |v169|, v171
	v_add_u32_e32 v169, v132, v144
	s_barrier
	ds_write_b64 v169, v[82:83]
	v_add_u32_e32 v82, v132, v145
	ds_write_b64 v82, v[84:85]
	v_add_u32_e32 v82, v132, v146
	ds_write_b64 v82, v[86:87]
	v_add_u32_e32 v82, v132, v147
	ds_write_b64 v82, v[88:89]
	v_add_u32_e32 v82, v132, v148
	ds_write_b64 v82, v[90:91]
	v_add_u32_e32 v82, v132, v149
	ds_write_b64 v82, v[198:199]
	v_add_u32_e32 v82, v132, v150
	ds_write_b64 v82, v[208:209]
	v_add_u32_e32 v82, v132, v151
	ds_write_b64 v82, v[190:191]
	v_add_u32_e32 v90, s92, v125
	ds_read_b128 v[82:85], v90
	ds_read_b128 v[86:89], v90 offset:4096
	ds_read_b128 v[172:175], v90 offset:8192
	ds_read_b128 v[178:181], v90 offset:12288
	s_waitcnt lgkmcnt(3)
	v_mfma_f32_16x16x32_bf16 v[82:85], v[82:85], v[28:31], 0
	s_waitcnt lgkmcnt(2)
	v_mfma_f32_16x16x32_bf16 v[86:89], v[86:89], v[28:31], 0
	s_waitcnt lgkmcnt(1)
	v_mfma_f32_16x16x32_bf16 v[172:175], v[172:175], v[28:31], 0
	s_waitcnt lgkmcnt(0)
	v_mfma_f32_16x16x32_bf16 v[178:181], v[178:181], v[28:31], 0
	ds_read_b128 v[182:185], v90 offset:16384
	ds_read_b128 v[186:189], v90 offset:20480
	ds_read_b128 v[190:193], v90 offset:24576
	ds_read_b128 v[194:197], v90 offset:28672
	s_waitcnt lgkmcnt(3)
	v_mfma_f32_16x16x32_bf16 v[182:185], v[182:185], v[28:31], 0
	s_waitcnt lgkmcnt(2)
	v_mfma_f32_16x16x32_bf16 v[186:189], v[186:189], v[28:31], 0
	s_waitcnt lgkmcnt(1)
	v_mfma_f32_16x16x32_bf16 v[190:193], v[190:193], v[28:31], 0
	s_waitcnt lgkmcnt(0)
	v_mfma_f32_16x16x32_bf16 v[28:31], v[194:197], v[28:31], 0
	v_add_u32_e32 v90, s92, v127
	ds_read_b128 v[234:237], v90
	ds_read_b128 v[194:197], v90 offset:4096
	ds_read_b128 v[218:221], v90 offset:8192
	ds_read_b128 v[222:225], v90 offset:12288
	ds_read_b128 v[226:229], v90 offset:16384
	ds_read_b128 v[230:233], v90 offset:20480
	s_waitcnt lgkmcnt(5)
	v_mfma_f32_16x16x32_bf16 v[82:85], v[234:237], v[24:27], v[82:85]
	ds_read_b128 v[234:237], v90 offset:24576
	s_waitcnt lgkmcnt(5)
	v_mfma_f32_16x16x32_bf16 v[86:89], v[194:197], v[24:27], v[86:89]
	ds_read_b128 v[194:197], v90 offset:28672
	s_waitcnt lgkmcnt(5)
	v_mfma_f32_16x16x32_bf16 v[172:175], v[218:221], v[24:27], v[172:175]
	s_nop 0
	s_waitcnt lgkmcnt(4)
	v_mfma_f32_16x16x32_bf16 v[178:181], v[222:225], v[24:27], v[178:181]
	s_nop 0
	s_waitcnt lgkmcnt(3)
	v_mfma_f32_16x16x32_bf16 v[182:185], v[226:229], v[24:27], v[182:185]
	s_nop 0
	s_waitcnt lgkmcnt(2)
	v_mfma_f32_16x16x32_bf16 v[186:189], v[230:233], v[24:27], v[186:189]
	s_nop 0
	s_waitcnt lgkmcnt(1)
	v_mfma_f32_16x16x32_bf16 v[190:193], v[234:237], v[24:27], v[190:193]
	s_nop 0
	s_waitcnt lgkmcnt(0)
	v_mfma_f32_16x16x32_bf16 v[24:27], v[194:197], v[24:27], v[28:31]
	s_nop 0
	v_add_u32_e32 v90, s92, v129
	s_nop 1
	ds_read_b128 v[28:31], v90
	s_waitcnt lgkmcnt(0)
; #define Q_LOAD(j) do { const size_t r = (size_t)(rfirst + rstep * ((j) * 128 + wid * 16 + li)); \
;           _Pragma("unroll") for (int ks = 0; ks < 4; ++ks) qf[ks] = *(const bf16x8*)(Q0 + r * 512 + h * 128 + ks * 32 + kq * 8); } while (0)
; template <int SPLIT> __device__ __forceinline__ void scan_item(const Params& p, unsigned char* smem, const int item, const int vh) {
;     ...
;             mm16<NBV>(acc2, CS + vh * 16384, qf, lane);
;             __builtin_amdgcn_sched_barrier(0);
;             Q_LOAD(jn);
; #pragma unroll
;             for (int nb = 0; nb < NBV; ++nb) acc2[nb] *= exl;
;             __builtin_amdgcn_sched_barrier(0);
;             { bf16x8 pf[4]; ldfrag(pf, KP, wid, lane); mm16<NBV>(acc2, VT + vh * 16384, pf, lane); }
	v_mfma_f32_16x16x32_bf16 v[28:31], v[28:31], v[20:23], v[82:85]
	s_nop 2
	ds_read_b128 v[82:85], v90 offset:4096
	s_waitcnt lgkmcnt(0)
	v_mfma_f32_16x16x32_bf16 v[82:85], v[82:85], v[20:23], v[86:89]
	s_nop 2
	ds_read_b128 v[86:89], v90 offset:8192
	s_waitcnt lgkmcnt(0)
	v_mfma_f32_16x16x32_bf16 v[86:89], v[86:89], v[20:23], v[172:175]
	s_nop 2
	ds_read_b128 v[172:175], v90 offset:12288
	s_waitcnt lgkmcnt(0)
	v_mfma_f32_16x16x32_bf16 v[172:175], v[172:175], v[20:23], v[178:181]
	s_nop 2
	ds_read_b128 v[178:181], v90 offset:16384
	s_waitcnt lgkmcnt(0)
	v_mfma_f32_16x16x32_bf16 v[178:181], v[178:181], v[20:23], v[182:185]
	s_nop 2
	ds_read_b128 v[182:185], v90 offset:20480
	s_waitcnt lgkmcnt(0)
	v_mfma_f32_16x16x32_bf16 v[182:185], v[182:185], v[20:23], v[186:189]
	s_nop 2
	ds_read_b128 v[186:189], v90 offset:24576
	s_waitcnt lgkmcnt(0)
	v_mfma_f32_16x16x32_bf16 v[186:189], v[186:189], v[20:23], v[190:193]
	s_nop 2
	ds_read_b128 v[190:193], v90 offset:28672
	s_waitcnt lgkmcnt(0)
	v_mfma_f32_16x16x32_bf16 v[20:23], v[190:193], v[20:23], v[24:27]
	v_add_u32_e32 v90, s92, v131
	s_nop 1
	ds_read_b128 v[234:237], v90
	ds_read_b128 v[24:27], v90 offset:4096
	ds_read_b128 v[218:221], v90 offset:8192
	ds_read_b128 v[222:225], v90 offset:12288
	ds_read_b128 v[226:229], v90 offset:16384
	ds_read_b128 v[230:233], v90 offset:20480
	s_waitcnt lgkmcnt(5)
	v_mfma_f32_16x16x32_bf16 v[190:193], v[234:237], v[12:15], v[28:31]
	ds_read_b128 v[234:237], v90 offset:24576
	s_waitcnt lgkmcnt(5)
	v_mfma_f32_16x16x32_bf16 v[82:85], v[24:27], v[12:15], v[82:85]
	ds_read_b128 v[24:27], v90 offset:28672
	s_waitcnt lgkmcnt(5)
	v_mfma_f32_16x16x32_bf16 v[86:89], v[218:221], v[12:15], v[86:89]
	s_nop 0
	s_waitcnt lgkmcnt(4)
	v_mfma_f32_16x16x32_bf16 v[172:175], v[222:225], v[12:15], v[172:175]
	s_nop 0
	s_waitcnt lgkmcnt(3)
	v_mfma_f32_16x16x32_bf16 v[178:181], v[226:229], v[12:15], v[178:181]
	s_nop 0
	s_waitcnt lgkmcnt(2)
	v_mfma_f32_16x16x32_bf16 v[182:185], v[230:233], v[12:15], v[182:185]
	s_nop 0
	s_waitcnt lgkmcnt(1)
	v_mfma_f32_16x16x32_bf16 v[186:189], v[234:237], v[12:15], v[186:189]
	s_nop 0
	s_waitcnt lgkmcnt(0)
	v_mfma_f32_16x16x32_bf16 v[194:197], v[24:27], v[12:15], v[20:23]
	s_nop 0
	v_add_u32_e32 v12, s0, v114
	v_mul_lo_u32 v12, v12, s3
	v_add_u32_e32 v12, s33, v12
	v_ashrrev_i32_e32 v13, 31, v12
	v_lshlrev_b64 v[12:13], 10, v[12:13]
	v_lshl_add_u64 v[12:13], v[104:105], 0, v[12:13]
	global_load_dwordx4 v[28:31], v[12:13], off
	global_load_dwordx4 v[24:27], v[12:13], off offset:64
	global_load_dwordx4 v[20:23], v[12:13], off offset:128
	s_nop 0
	global_load_dwordx4 v[12:15], v[12:13], off offset:192
	v_pk_mul_f32 v[82:83], v[80:81], v[82:83] op_sel_hi:[0,1]
	v_pk_mul_f32 v[192:193], v[80:81], v[192:193] op_sel_hi:[0,1]
	v_pk_mul_f32 v[190:191], v[80:81], v[190:191] op_sel_hi:[0,1]
	v_pk_mul_f32 v[84:85], v[80:81], v[84:85] op_sel_hi:[0,1]
	v_pk_mul_f32 v[88:89], v[80:81], v[88:89] op_sel_hi:[0,1]
	v_pk_mul_f32 v[86:87], v[80:81], v[86:87] op_sel_hi:[0,1]
	v_pk_mul_f32 v[174:175], v[80:81], v[174:175] op_sel_hi:[0,1]
	v_pk_mul_f32 v[172:173], v[80:81], v[172:173] op_sel_hi:[0,1]
	v_pk_mul_f32 v[180:181], v[80:81], v[180:181] op_sel_hi:[0,1]
	v_pk_mul_f32 v[178:179], v[80:81], v[178:179] op_sel_hi:[0,1]
	v_pk_mul_f32 v[184:185], v[80:81], v[184:185] op_sel_hi:[0,1]
	v_pk_mul_f32 v[182:183], v[80:81], v[182:183] op_sel_hi:[0,1]
	v_pk_mul_f32 v[188:189], v[80:81], v[188:189] op_sel_hi:[0,1]
	v_rcp_f32_e32 v171, v168
	v_pk_mul_f32 v[186:187], v[80:81], v[186:187] op_sel_hi:[0,1]
	v_pk_mul_f32 v[196:197], v[80:81], v[196:197] op_sel_hi:[0,1]
	v_pk_mul_f32 v[194:195], v[80:81], v[194:195] op_sel_hi:[0,1]
	ds_read_b128 v[198:201], v81 offset:32768
	ds_read_b128 v[202:205], v81 offset:36864
	ds_read_b128 v[206:209], v159
	ds_read_b128 v[210:213], v160
	s_waitcnt lgkmcnt(1)
	v_mfma_f32_16x16x32_bf16 v[190:193], v[198:201], v[206:209], v[190:193]
	ds_read_b128 v[198:201], v81 offset:40960
	v_mfma_f32_16x16x32_bf16 v[82:85], v[202:205], v[206:209], v[82:85]
	ds_read_b128 v[202:205], v81 offset:45056
	s_waitcnt lgkmcnt(1)
	v_mfma_f32_16x16x32_bf16 v[86:89], v[198:201], v[206:209], v[86:89]
	ds_read_b128 v[198:201], v161
	ds_read_b128 v[214:217], v162
	s_waitcnt lgkmcnt(2)
	v_mfma_f32_16x16x32_bf16 v[172:175], v[202:205], v[206:209], v[172:175]
	ds_read_b128 v[226:229], v81 offset:49152
	ds_read_b128 v[230:233], v81 offset:53248
	ds_read_b128 v[234:237], v81 offset:57344
	ds_read_b128 v[202:205], v81 offset:61440
	s_waitcnt lgkmcnt(3)
	v_mfma_f32_16x16x32_bf16 v[178:181], v[226:229], v[206:209], v[178:181]
	s_nop 0
	s_waitcnt lgkmcnt(2)
	v_mfma_f32_16x16x32_bf16 v[182:185], v[230:233], v[206:209], v[182:185]
	s_nop 0
	s_waitcnt lgkmcnt(1)
	v_mfma_f32_16x16x32_bf16 v[186:189], v[234:237], v[206:209], v[186:189]
	s_nop 0
	s_waitcnt lgkmcnt(0)
	v_mfma_f32_16x16x32_bf16 v[194:197], v[202:205], v[206:209], v[194:197]
	s_nop 0
	ds_read_b128 v[202:205], v165 offset:32768
	s_waitcnt lgkmcnt(0)
	v_mfma_f32_16x16x32_bf16 v[190:193], v[202:205], v[210:213], v[190:193]
	ds_read_b128 v[202:205], v165 offset:36864
	s_waitcnt lgkmcnt(0)
	v_mfma_f32_16x16x32_bf16 v[80:83], v[202:205], v[210:213], v[82:85]
	ds_read_b128 v[202:205], v165 offset:40960
	s_waitcnt lgkmcnt(0)
	v_mfma_f32_16x16x32_bf16 v[84:87], v[202:205], v[210:213], v[86:89]
	s_nop 2
	ds_read_b128 v[88:91], v165 offset:45056
	s_waitcnt lgkmcnt(0)
	v_mfma_f32_16x16x32_bf16 v[88:91], v[88:91], v[210:213], v[172:175]
	s_nop 2
	ds_read_b128 v[172:175], v165 offset:49152
	s_waitcnt lgkmcnt(0)
	v_mfma_f32_16x16x32_bf16 v[172:175], v[172:175], v[210:213], v[178:181]
	s_nop 2
	ds_read_b128 v[178:181], v165 offset:53248
	s_waitcnt lgkmcnt(0)
; __device__ __forceinline__ unsigned cvt_pk(float lo, float hi) { unsigned r; asm volatile("v_cvt_pk_bf16_f32 %0, %1, %2" : "=v"(r) : "v"(lo), "v"(hi)); return r; }
; template <int SPLIT> __device__ __forceinline__ void scan_item(const Params& p, unsigned char* smem, const int item, const int vh) {
;     ...
;             { bf16_t* hp = P0 + rowl * LDP + dir * 512 + h * 128 + vh * 64 + kq * 4;
; #pragma unroll
;               for (int nb = 0; nb < NBV; ++nb) { u32x2 o; o.x = cvt_pk(acc2[nb][0] * hinv, acc2[nb][1] * hinv); o.y = cvt_pk(acc2[nb][2] * hinv, acc2[nb][3] * hinv);
;                   *(u32x2*)(hp + nb * 16) = o; } }
;             __builtin_amdgcn_sched_barrier(0);
;             float nnew;
;             { bf16x8 vf[4]; ldfrag(vf, VT, vblk, lane);
; #pragma unroll
;               for (int nb = 0; nb < NBV; ++nb) Cacc[nb] *= decay;
;               mm16<NBV>(Cacc, KT + kh * 16384, vf, lane);
	v_mfma_f32_16x16x32_bf16 v[178:181], v[178:181], v[210:213], v[182:185]
	s_nop 2
	ds_read_b128 v[182:185], v165 offset:57344
	s_waitcnt lgkmcnt(0)
	v_mfma_f32_16x16x32_bf16 v[182:185], v[182:185], v[210:213], v[186:189]
	s_nop 2
	ds_read_b128 v[186:189], v165 offset:61440
	s_waitcnt lgkmcnt(0)
	v_mfma_f32_16x16x32_bf16 v[186:189], v[186:189], v[210:213], v[194:197]
	s_nop 2
	ds_read_b128 v[234:237], v166 offset:32768
	ds_read_b128 v[194:197], v166 offset:36864
	ds_read_b128 v[218:221], v166 offset:40960
	ds_read_b128 v[222:225], v166 offset:45056
	ds_read_b128 v[226:229], v166 offset:49152
	ds_read_b128 v[230:233], v166 offset:53248
	s_waitcnt lgkmcnt(5)
	v_mfma_f32_16x16x32_bf16 v[190:193], v[234:237], v[198:201], v[190:193]
	ds_read_b128 v[234:237], v166 offset:57344
	s_waitcnt lgkmcnt(5)
	v_mfma_f32_16x16x32_bf16 v[80:83], v[194:197], v[198:201], v[80:83]
	ds_read_b128 v[194:197], v166 offset:61440
	s_waitcnt lgkmcnt(5)
	v_mfma_f32_16x16x32_bf16 v[84:87], v[218:221], v[198:201], v[84:87]
	s_nop 0
	s_waitcnt lgkmcnt(4)
	v_mfma_f32_16x16x32_bf16 v[88:91], v[222:225], v[198:201], v[88:91]
	s_nop 0
	s_waitcnt lgkmcnt(3)
	v_mfma_f32_16x16x32_bf16 v[172:175], v[226:229], v[198:201], v[172:175]
	s_nop 0
	s_waitcnt lgkmcnt(2)
	v_mfma_f32_16x16x32_bf16 v[178:181], v[230:233], v[198:201], v[178:181]
	s_nop 0
	s_waitcnt lgkmcnt(1)
	v_mfma_f32_16x16x32_bf16 v[182:185], v[234:237], v[198:201], v[182:185]
	s_nop 0
	s_waitcnt lgkmcnt(0)
	v_mfma_f32_16x16x32_bf16 v[186:189], v[194:197], v[198:201], v[186:189]
	s_nop 0
	ds_read_b128 v[218:221], v167 offset:32768
	ds_read_b128 v[222:225], v167 offset:36864
	ds_read_b128 v[226:229], v167 offset:40960
	ds_read_b128 v[230:233], v167 offset:45056
	ds_read_b128 v[234:237], v167 offset:49152
	ds_read_b128 v[194:197], v167 offset:53248
	s_waitcnt lgkmcnt(5)
	v_mfma_f32_16x16x32_bf16 v[190:193], v[218:221], v[214:217], v[190:193]
	s_nop 0
	s_waitcnt lgkmcnt(4)
	v_mfma_f32_16x16x32_bf16 v[80:83], v[222:225], v[214:217], v[80:83]
	s_nop 0
	s_waitcnt lgkmcnt(3)
	v_mfma_f32_16x16x32_bf16 v[84:87], v[226:229], v[214:217], v[84:87]
	s_nop 0
	s_waitcnt lgkmcnt(2)
	v_mfma_f32_16x16x32_bf16 v[88:91], v[230:233], v[214:217], v[88:91]
	s_nop 0
	s_waitcnt lgkmcnt(1)
	v_mfma_f32_16x16x32_bf16 v[172:175], v[234:237], v[214:217], v[172:175]
	s_nop 0
	s_waitcnt lgkmcnt(0)
	v_mfma_f32_16x16x32_bf16 v[178:181], v[194:197], v[214:217], v[178:181]
	s_nop 0
	ds_read_b128 v[194:197], v167 offset:57344
	ds_read_b128 v[166:169], v167 offset:61440
	s_waitcnt lgkmcnt(1)
	v_mfma_f32_16x16x32_bf16 v[182:185], v[194:197], v[214:217], v[182:185]
	s_waitcnt lgkmcnt(0)
	v_mfma_f32_16x16x32_bf16 v[166:169], v[166:169], v[214:217], v[186:189]
	s_nop 2
	v_mad_i64_i32 v[186:187], s[4:5], v152, s88, v[106:107]
	v_mul_f32_e32 v165, v171, v190
	v_mul_f32_e32 v177, v171, v191
	v_mul_f32_e32 v80, v171, v80
	v_mul_f32_e32 v81, v171, v81
	v_cvt_pk_bf16_f32 v188, v165, v177
	v_mul_f32_e32 v165, v171, v192
	v_mul_f32_e32 v177, v171, v193
	v_cvt_pk_bf16_f32 v189, v165, v177
	global_store_dwordx2 v[186:187], v[188:189], off
	v_cvt_pk_bf16_f32 v80, v80, v81
	v_mul_f32_e32 v81, v171, v82
	v_mul_f32_e32 v82, v171, v83
	v_cvt_pk_bf16_f32 v81, v81, v82
	global_store_dwordx2 v[186:187], v[80:81], off offset:32
	v_mul_f32_e32 v80, v171, v84
	v_mul_f32_e32 v81, v171, v85
	v_cvt_pk_bf16_f32 v80, v80, v81
	v_mul_f32_e32 v81, v171, v86
	v_mul_f32_e32 v82, v171, v87
	v_cvt_pk_bf16_f32 v81, v81, v82
	global_store_dwordx2 v[186:187], v[80:81], off offset:64
	v_mul_f32_e32 v80, v171, v88
	v_mul_f32_e32 v81, v171, v89
	v_cvt_pk_bf16_f32 v80, v80, v81
	v_mul_f32_e32 v81, v171, v90
	v_mul_f32_e32 v82, v171, v91
	v_cvt_pk_bf16_f32 v81, v81, v82
	global_store_dwordx2 v[186:187], v[80:81], off offset:96
	v_mul_f32_e32 v80, v171, v172
	v_mul_f32_e32 v81, v171, v173
	v_cvt_pk_bf16_f32 v80, v80, v81
	v_mul_f32_e32 v81, v171, v174
	v_mul_f32_e32 v82, v171, v175
	v_cvt_pk_bf16_f32 v81, v81, v82
	global_store_dwordx2 v[186:187], v[80:81], off offset:128
	v_mul_f32_e32 v80, v171, v178
	v_mul_f32_e32 v81, v171, v179
	v_cvt_pk_bf16_f32 v80, v80, v81
	v_mul_f32_e32 v81, v171, v180
	v_mul_f32_e32 v82, v171, v181
	v_cvt_pk_bf16_f32 v81, v81, v82
	global_store_dwordx2 v[186:187], v[80:81], off offset:160
	v_mul_f32_e32 v80, v171, v182
	v_mul_f32_e32 v81, v171, v183
	v_cvt_pk_bf16_f32 v80, v80, v81
	v_mul_f32_e32 v81, v171, v184
	v_mul_f32_e32 v82, v171, v185
	v_cvt_pk_bf16_f32 v81, v81, v82
	global_store_dwordx2 v[186:187], v[80:81], off offset:192
	v_mul_f32_e32 v80, v171, v166
	v_mul_f32_e32 v81, v171, v167
	v_cvt_pk_bf16_f32 v80, v80, v81
	v_mul_f32_e32 v81, v171, v168
	v_mul_f32_e32 v82, v171, v169
	v_cvt_pk_bf16_f32 v81, v81, v82
	global_store_dwordx2 v[186:187], v[80:81], off offset:224
	v_add_u32_e32 v165, s89, v125
	ds_read_b128 v[166:169], v159 offset:32768
	ds_read_b128 v[88:91], v160 offset:32768
	ds_read_b128 v[84:87], v161 offset:32768
	ds_read_b128 v[80:83], v162 offset:32768
	ds_read_b128 v[172:175], v165
	v_pk_mul_f32 v[58:59], v[58:59], v[112:113] op_sel_hi:[1,0]
	v_pk_mul_f32 v[56:57], v[56:57], v[112:113] op_sel_hi:[1,0]
	v_pk_mul_f32 v[50:51], v[50:51], v[112:113] op_sel_hi:[1,0]
	v_pk_mul_f32 v[48:49], v[48:49], v[112:113] op_sel_hi:[1,0]
	v_pk_mul_f32 v[54:55], v[54:55], v[112:113] op_sel_hi:[1,0]
	v_pk_mul_f32 v[52:53], v[52:53], v[112:113] op_sel_hi:[1,0]
	v_pk_mul_f32 v[62:63], v[62:63], v[112:113] op_sel_hi:[1,0]
	s_waitcnt lgkmcnt(0)
; template <int SPLIT> __device__ __forceinline__ void scan_item(const Params& p, unsigned char* smem, const int item, const int vh) {
;     ...
;               mm16<NBV>(Cacc, KT + kh * 16384, vf, lane);
	v_mfma_f32_16x16x32_bf16 v[56:59], v[172:175], v[166:169], v[56:59]
	ds_read_b128 v[172:175], v165 offset:4096
	v_pk_mul_f32 v[60:61], v[60:61], v[112:113] op_sel_hi:[1,0]
	v_pk_mul_f32 v[66:67], v[66:67], v[112:113] op_sel_hi:[1,0]
	v_pk_mul_f32 v[64:65], v[64:65], v[112:113] op_sel_hi:[1,0]
	v_pk_mul_f32 v[70:71], v[70:71], v[112:113] op_sel_hi:[1,0]
	v_pk_mul_f32 v[68:69], v[68:69], v[112:113] op_sel_hi:[1,0]
	v_pk_mul_f32 v[74:75], v[74:75], v[112:113] op_sel_hi:[1,0]
	s_waitcnt lgkmcnt(0)
	v_mfma_f32_16x16x32_bf16 v[48:51], v[172:175], v[166:169], v[48:51]
	ds_read_b128 v[172:175], v165 offset:8192
	v_pk_mul_f32 v[72:73], v[72:73], v[112:113] op_sel_hi:[1,0]
	v_pk_mul_f32 v[78:79], v[78:79], v[112:113] op_sel_hi:[1,0]
	v_pk_mul_f32 v[76:77], v[76:77], v[112:113] op_sel_hi:[1,0]
	s_waitcnt lgkmcnt(0)
	v_mfma_f32_16x16x32_bf16 v[52:55], v[172:175], v[166:169], v[52:55]
	ds_read_b128 v[222:225], v165 offset:12288
	ds_read_b128 v[226:229], v165 offset:16384
	ds_read_b128 v[230:233], v165 offset:20480
	ds_read_b128 v[234:237], v165 offset:24576
	ds_read_b128 v[172:175], v165 offset:28672
	s_waitcnt lgkmcnt(4)
	v_mfma_f32_16x16x32_bf16 v[60:63], v[222:225], v[166:169], v[60:63]
	s_nop 0
	s_waitcnt lgkmcnt(3)
	v_mfma_f32_16x16x32_bf16 v[64:67], v[226:229], v[166:169], v[64:67]
	s_nop 0
	s_waitcnt lgkmcnt(2)
	v_mfma_f32_16x16x32_bf16 v[68:71], v[230:233], v[166:169], v[68:71]
	s_nop 0
	s_waitcnt lgkmcnt(1)
	v_mfma_f32_16x16x32_bf16 v[72:75], v[234:237], v[166:169], v[72:75]
	s_nop 0
	s_waitcnt lgkmcnt(0)
	v_mfma_f32_16x16x32_bf16 v[76:79], v[172:175], v[166:169], v[76:79]
	s_nop 0
	v_add_u32_e32 v165, s89, v127
	ds_read_b128 v[234:237], v165
	ds_read_b128 v[166:169], v165 offset:4096
	ds_read_b128 v[218:221], v165 offset:8192
	ds_read_b128 v[222:225], v165 offset:12288
	ds_read_b128 v[226:229], v165 offset:16384
	ds_read_b128 v[230:233], v165 offset:20480
	s_waitcnt lgkmcnt(5)
	v_mfma_f32_16x16x32_bf16 v[56:59], v[234:237], v[88:91], v[56:59]
	ds_read_b128 v[234:237], v165 offset:24576
	s_waitcnt lgkmcnt(5)
	v_mfma_f32_16x16x32_bf16 v[48:51], v[166:169], v[88:91], v[48:51]
	ds_read_b128 v[166:169], v165 offset:28672
	s_waitcnt lgkmcnt(5)
	v_mfma_f32_16x16x32_bf16 v[52:55], v[218:221], v[88:91], v[52:55]
	s_nop 0
	s_waitcnt lgkmcnt(4)
	v_mfma_f32_16x16x32_bf16 v[60:63], v[222:225], v[88:91], v[60:63]
	s_nop 0
	s_waitcnt lgkmcnt(3)
	v_mfma_f32_16x16x32_bf16 v[64:67], v[226:229], v[88:91], v[64:67]
	s_nop 0
	s_waitcnt lgkmcnt(2)
	v_mfma_f32_16x16x32_bf16 v[68:71], v[230:233], v[88:91], v[68:71]
	s_nop 0
	s_waitcnt lgkmcnt(1)
	v_mfma_f32_16x16x32_bf16 v[72:75], v[234:237], v[88:91], v[72:75]
	s_nop 0
	s_waitcnt lgkmcnt(0)
	v_mfma_f32_16x16x32_bf16 v[76:79], v[166:169], v[88:91], v[76:79]
	s_nop 0
	v_add_u32_e32 v165, s89, v129
	ds_read_b128 v[234:237], v165
	ds_read_b128 v[88:91], v165 offset:4096
	ds_read_b128 v[218:221], v165 offset:8192
	ds_read_b128 v[222:225], v165 offset:12288
	ds_read_b128 v[226:229], v165 offset:16384
	ds_read_b128 v[230:233], v165 offset:20480
	s_waitcnt lgkmcnt(5)
	v_mfma_f32_16x16x32_bf16 v[56:59], v[234:237], v[84:87], v[56:59]
	ds_read_b128 v[234:237], v165 offset:24576
	s_waitcnt lgkmcnt(5)
	v_mfma_f32_16x16x32_bf16 v[48:51], v[88:91], v[84:87], v[48:51]
	ds_read_b128 v[88:91], v165 offset:28672
	s_waitcnt lgkmcnt(5)
	v_mfma_f32_16x16x32_bf16 v[52:55], v[218:221], v[84:87], v[52:55]
	s_nop 0
	s_waitcnt lgkmcnt(4)
	v_mfma_f32_16x16x32_bf16 v[60:63], v[222:225], v[84:87], v[60:63]
	s_nop 0
	s_waitcnt lgkmcnt(3)
	v_mfma_f32_16x16x32_bf16 v[64:67], v[226:229], v[84:87], v[64:67]
	s_nop 0
	s_waitcnt lgkmcnt(2)
	v_mfma_f32_16x16x32_bf16 v[68:71], v[230:233], v[84:87], v[68:71]
	s_nop 0
	s_waitcnt lgkmcnt(1)
	v_mfma_f32_16x16x32_bf16 v[72:75], v[234:237], v[84:87], v[72:75]
	s_nop 0
	s_waitcnt lgkmcnt(0)
	v_mfma_f32_16x16x32_bf16 v[76:79], v[88:91], v[84:87], v[76:79]
	s_nop 0
	v_add_u32_e32 v88, s89, v131
	ds_read_b128 v[234:237], v88
	ds_read_b128 v[84:87], v88 offset:4096
	ds_read_b128 v[218:221], v88 offset:8192
	ds_read_b128 v[222:225], v88 offset:12288
	ds_read_b128 v[226:229], v88 offset:16384
	ds_read_b128 v[230:233], v88 offset:20480
	s_waitcnt lgkmcnt(5)
	v_mfma_f32_16x16x32_bf16 v[56:59], v[234:237], v[80:83], v[56:59]
	ds_read_b128 v[234:237], v88 offset:24576
	s_waitcnt lgkmcnt(5)
; __device__ __forceinline__ unsigned cvt_pk(float lo, float hi) { unsigned r; asm volatile("v_cvt_pk_bf16_f32 %0, %1, %2" : "=v"(r) : "v"(lo), "v"(hi)); return r; }
; __device__ __forceinline__ float bflo(unsigned w) { return __uint_as_float(w << 16); }
; __device__ __forceinline__ float bfhi(unsigned w) { return __uint_as_float(w & 0xffff0000u); }
; template <int SPLIT> __device__ __forceinline__ void scan_item(const Params& p, unsigned char* smem, const int item, const int vh) {
;     ...
;               mm16<NBV>(Cacc, KT + kh * 16384, vf, lane);
;               float part = 0.f;
; #pragma unroll
;               for (int ks = 0; ks < 4; ++ks) { const u32x4 kw = *(const u32x4*)(KT + swz(wid * 16 + li, ks * 4 + kq));
;                   part += bflo(kw.x) + bfhi(kw.x) + bflo(kw.y) + bfhi(kw.y) + bflo(kw.z) + bfhi(kw.z) + bflo(kw.w) + bfhi(kw.w); }
;               part += __shfl_xor(part, 16); part += __shfl_xor(part, 32);
;               nnew = decay * n_s[wid * 16 + li] + part; }
;             __syncthreads();
; #pragma unroll
;             for (int nb = 0; nb < NBV; ++nb) { u32x2 o; o.x = cvt_pk(Cacc[nb][0], Cacc[nb][1]); o.y = cvt_pk(Cacc[nb][2], Cacc[nb][3]);
;                 *(u32x2*)(CS + swz(vblk * 16 + li, (kh * 4 + nb) * 2 + (kq >> 1)) + (kq & 1) * 8) = o; }
;             if (kq == 0) n_s[wid * 16 + li] = nnew;
	v_mfma_f32_16x16x32_bf16 v[48:51], v[84:87], v[80:83], v[48:51]
	ds_read_b128 v[84:87], v88 offset:28672
	s_waitcnt lgkmcnt(5)
	v_mfma_f32_16x16x32_bf16 v[52:55], v[218:221], v[80:83], v[52:55]
	s_nop 0
	s_waitcnt lgkmcnt(4)
	v_mfma_f32_16x16x32_bf16 v[60:63], v[222:225], v[80:83], v[60:63]
	s_nop 0
	s_waitcnt lgkmcnt(3)
	v_mfma_f32_16x16x32_bf16 v[64:67], v[226:229], v[80:83], v[64:67]
	s_nop 0
	s_waitcnt lgkmcnt(2)
	v_mfma_f32_16x16x32_bf16 v[68:71], v[230:233], v[80:83], v[68:71]
	s_nop 0
	s_waitcnt lgkmcnt(1)
	v_mfma_f32_16x16x32_bf16 v[72:75], v[234:237], v[80:83], v[72:75]
	s_nop 0
	s_waitcnt lgkmcnt(0)
	v_mfma_f32_16x16x32_bf16 v[76:79], v[84:87], v[80:83], v[76:79]
	s_nop 0
	v_add_u32_e32 v80, v133, v124
	ds_read_b128 v[80:83], v80
	s_waitcnt lgkmcnt(0)
	v_lshlrev_b32_e32 v84, 16, v80
	v_and_b32_e32 v80, 0xffff0000, v80
	v_add_f32_e32 v80, v84, v80
	v_lshlrev_b32_e32 v84, 16, v81
	v_add_f32_e32 v80, v80, v84
	v_and_b32_e32 v81, 0xffff0000, v81
	v_add_f32_e32 v80, v80, v81
	v_lshlrev_b32_e32 v81, 16, v82
	v_add_f32_e32 v80, v80, v81
	v_and_b32_e32 v81, 0xffff0000, v82
	v_add_f32_e32 v80, v80, v81
	v_lshlrev_b32_e32 v81, 16, v83
	v_add_f32_e32 v80, v80, v81
	v_and_b32_e32 v81, 0xffff0000, v83
	v_add_f32_e32 v80, v80, v81
	v_add_f32_e32 v84, 0, v80
	v_add_u32_e32 v80, v133, v126
	ds_read_b128 v[80:83], v80
	s_waitcnt lgkmcnt(0)
	v_lshlrev_b32_e32 v85, 16, v80
	v_and_b32_e32 v80, 0xffff0000, v80
	v_add_f32_e32 v80, v85, v80
	v_lshlrev_b32_e32 v85, 16, v81
	v_add_f32_e32 v80, v80, v85
	v_and_b32_e32 v81, 0xffff0000, v81
	v_add_f32_e32 v80, v80, v81
	v_lshlrev_b32_e32 v81, 16, v82
	v_add_f32_e32 v80, v80, v81
	v_and_b32_e32 v81, 0xffff0000, v82
	v_add_f32_e32 v80, v80, v81
	v_lshlrev_b32_e32 v81, 16, v83
	v_add_f32_e32 v80, v80, v81
	v_and_b32_e32 v81, 0xffff0000, v83
	v_add_f32_e32 v80, v80, v81
	v_add_f32_e32 v84, v84, v80
	v_add_u32_e32 v80, v133, v128
	ds_read_b128 v[80:83], v80
	s_waitcnt lgkmcnt(0)
	v_lshlrev_b32_e32 v85, 16, v80
	v_and_b32_e32 v80, 0xffff0000, v80
	v_add_f32_e32 v80, v85, v80
	v_lshlrev_b32_e32 v85, 16, v81
	v_add_f32_e32 v80, v80, v85
	v_and_b32_e32 v81, 0xffff0000, v81
	v_add_f32_e32 v80, v80, v81
	v_lshlrev_b32_e32 v81, 16, v82
	v_add_f32_e32 v80, v80, v81
	v_and_b32_e32 v81, 0xffff0000, v82
	v_add_f32_e32 v80, v80, v81
	v_lshlrev_b32_e32 v81, 16, v83
	v_add_f32_e32 v80, v80, v81
	v_and_b32_e32 v81, 0xffff0000, v83
	v_add_f32_e32 v80, v80, v81
	v_add_f32_e32 v84, v84, v80
	v_add_u32_e32 v80, v133, v130
	ds_read_b128 v[80:83], v80
	s_waitcnt lgkmcnt(0)
	v_lshlrev_b32_e32 v85, 16, v80
	v_and_b32_e32 v80, 0xffff0000, v80
	v_add_f32_e32 v80, v85, v80
	v_lshlrev_b32_e32 v85, 16, v81
	v_add_f32_e32 v80, v80, v85
	v_and_b32_e32 v81, 0xffff0000, v81
	v_add_f32_e32 v80, v80, v81
	v_lshlrev_b32_e32 v81, 16, v82
	v_add_f32_e32 v80, v80, v81
	v_and_b32_e32 v81, 0xffff0000, v82
	v_add_f32_e32 v80, v80, v81
	v_lshlrev_b32_e32 v81, 16, v83
	v_add_f32_e32 v80, v80, v81
	v_and_b32_e32 v81, 0xffff0000, v83
	v_add_f32_e32 v80, v80, v81
	v_add_f32_e32 v80, v84, v80
	ds_bpermute_b32 v81, v164, v80
	v_add_u32_e32 v83, v135, v144
	ds_read_b32 v82, v134
	s_waitcnt lgkmcnt(0)
	s_barrier
	v_cvt_pk_bf16_f32 v84, v56, v57
	v_cvt_pk_bf16_f32 v85, v58, v59
	ds_write_b64 v83, v[84:85]
	v_add_u32_e32 v83, v135, v145
	v_add_f32_e32 v80, v80, v81
	v_cvt_pk_bf16_f32 v84, v48, v49
	v_cvt_pk_bf16_f32 v85, v50, v51
	ds_write_b64 v83, v[84:85]
	v_add_u32_e32 v83, v135, v146
	ds_bpermute_b32 v81, v95, v80
	v_cvt_pk_bf16_f32 v84, v52, v53
	v_cvt_pk_bf16_f32 v85, v54, v55
	ds_write_b64 v83, v[84:85]
	v_add_u32_e32 v83, v135, v147
	v_cvt_pk_bf16_f32 v84, v60, v61
	v_cvt_pk_bf16_f32 v85, v62, v63
	ds_write_b64 v83, v[84:85]
	v_add_u32_e32 v83, v135, v148
	v_cvt_pk_bf16_f32 v84, v64, v65
	v_cvt_pk_bf16_f32 v85, v66, v67
	ds_write_b64 v83, v[84:85]
	v_add_u32_e32 v83, v135, v149
	v_cvt_pk_bf16_f32 v84, v68, v69
	v_cvt_pk_bf16_f32 v85, v70, v71
	ds_write_b64 v83, v[84:85]
	v_add_u32_e32 v83, v135, v150
	v_cvt_pk_bf16_f32 v84, v72, v73
	v_cvt_pk_bf16_f32 v85, v74, v75
	ds_write_b64 v83, v[84:85]
	v_add_u32_e32 v83, v135, v151
	v_cvt_pk_bf16_f32 v84, v76, v77
	v_cvt_pk_bf16_f32 v85, v78, v79
	ds_write_b64 v83, v[84:85]
	s_and_saveexec_b64 s[86:87], s[8:9]
	s_cbranch_execz .LBB0_289
	s_waitcnt lgkmcnt(6)
	v_add_f32_e32 v80, v80, v81
	v_fmac_f32_e32 v80, v112, v82
	ds_write_b32 v134, v80
	s_branch .LBB0_289

; __device__ __forceinline__ unsigned cvt_pk(float lo, float hi) { unsigned r; asm volatile("v_cvt_pk_bf16_f32 %0, %1, %2" : "=v"(r) : "v"(lo), "v"(hi)); return r; }
; __device__ __forceinline__ float bflo(unsigned w) { return __uint_as_float(w << 16); }
; __device__ __forceinline__ float bfhi(unsigned w) { return __uint_as_float(w & 0xffff0000u); }
; template <int SPLIT> __device__ __forceinline__ void scan_item(const Params& p, unsigned char* smem, const int item, const int vh) {
;     ...
;             const float m_old = sc[0], M127 = sc[1];
;             const float decay = __expf(m_old - M127);
;             {
;                 const f32x4 a4 = *(const f32x4*)(a_s + sp * 4);
;                 float wsv[4];
; #pragma unroll
;                 for (int i = 0; i < 4; ++i) wsv[i] = __expf(a4[i] - M127);
; #pragma unroll
;                 for (int i = 0; i < 4; ++i) { const u32x4 k = kreg[i]; u32x4 w;
;                     w.x = cvt_pk(bflo(k.x) * wsv[i], bfhi(k.x) * wsv[i]); w.y = cvt_pk(bflo(k.y) * wsv[i], bfhi(k.y) * wsv[i]);
;                     w.z = cvt_pk(bflo(k.z) * wsv[i], bfhi(k.z) * wsv[i]); w.w = cvt_pk(bflo(k.w) * wsv[i], bfhi(k.w) * wsv[i]);
;                     *(u32x4*)(KP + swz(sp * 4 + i, ch)) = w; }
; #pragma unroll
;                 for (int e2 = 0; e2 < 4; ++e2) {
;                     const unsigned k0 = kreg[0][e2], k1 = kreg[1][e2], k2 = kreg[2][e2], k3 = kreg[3][e2];
;                     const unsigned v0 = vreg[0][e2], v1 = vreg[1][e2], v2 = vreg[2][e2], v3 = vreg[3][e2];
;                     const int d0 = ch * 8 + 2 * e2, d1 = d0 + 1; const int co = (sp & 1) * 8;
;                     u32x2 o;
;                     o.x = cvt_pk(bflo(k0) * wsv[0], bflo(k1) * wsv[1]); o.y = cvt_pk(bflo(k2) * wsv[2], bflo(k3) * wsv[3]);
;                     *(u32x2*)(KT + swz(d0, sp >> 1) + co) = o;
;                     o.x = cvt_pk(bfhi(k0) * wsv[0], bfhi(k1) * wsv[1]); o.y = cvt_pk(bfhi(k2) * wsv[2], bfhi(k3) * wsv[3]);
;                     *(u32x2*)(KT + swz(d1, sp >> 1) + co) = o;
;                     o.x = (v0 & 0xffffu) | (v1 << 16); o.y = (v2 & 0xffffu) | (v3 << 16);
;                     *(u32x2*)(VT + swz(d0, sp >> 1) + co) = o;
;                     o.x = (v0 >> 16) | (v1 & 0xffff0000u); o.y = (v2 >> 16) | (v3 & 0xffff0000u);
;                     *(u32x2*)(VT + swz(d1, sp >> 1) + co) = o;
;                 }
;             }
.LBB0_316:
	s_or_b64 exec, exec, s[86:87]
	v_mov_b32_e32 v67, s92
	s_waitcnt lgkmcnt(0)
	s_barrier
	ds_read_b64 v[86:87], v67
	ds_read_b128 v[88:91], v98
	s_waitcnt vmcnt(11)
	v_lshlrev_b32_e32 v92, 16, v45
	v_and_b32_e32 v45, 0xffff0000, v45
	v_lshlrev_b32_e32 v94, 16, v46
	v_and_b32_e32 v46, 0xffff0000, v46
	s_waitcnt lgkmcnt(0)
	v_sub_f32_e32 v67, v88, v87
	v_mul_f32_e32 v67, 0x3fb8aa3b, v67
	v_exp_f32_e32 v67, v67
	v_sub_f32_e32 v84, v89, v87
	v_mul_f32_e32 v84, 0x3fb8aa3b, v84
	v_exp_f32_e32 v84, v84
	v_sub_f32_e32 v88, v90, v87
	v_mul_f32_e32 v88, 0x3fb8aa3b, v88
	v_lshlrev_b32_e32 v90, 16, v44
	v_and_b32_e32 v44, 0xffff0000, v44
	v_exp_f32_e32 v88, v88
	v_sub_f32_e32 v89, v91, v87
	v_mul_f32_e32 v90, v67, v90
	v_mul_f32_e32 v91, v67, v44
	v_cvt_pk_bf16_f32 v44, v90, v91
	v_mul_f32_e32 v92, v67, v92
	v_mul_f32_e32 v93, v67, v45
	v_cvt_pk_bf16_f32 v45, v92, v93
	v_mul_f32_e32 v94, v67, v94
	v_mul_f32_e32 v95, v67, v46
	v_cvt_pk_bf16_f32 v46, v94, v95
	v_lshlrev_b32_e32 v151, 16, v47
	v_and_b32_e32 v47, 0xffff0000, v47
	v_mul_f32_e32 v89, 0x3fb8aa3b, v89
	v_mul_f32_e32 v151, v67, v151
	v_mul_f32_e32 v67, v67, v47
	v_cvt_pk_bf16_f32 v47, v151, v67
	ds_write_b128 v133, v[44:47]
	s_waitcnt vmcnt(10)
	v_lshlrev_b32_e32 v44, 16, v40
	v_and_b32_e32 v40, 0xffff0000, v40
	v_lshlrev_b32_e32 v46, 16, v41
	v_and_b32_e32 v41, 0xffff0000, v41
	v_lshlrev_b32_e32 v152, 16, v42
	v_and_b32_e32 v42, 0xffff0000, v42
	v_exp_f32_e32 v89, v89
	v_mul_f32_e32 v44, v84, v44
	v_mul_f32_e32 v45, v84, v40
	v_cvt_pk_bf16_f32 v40, v44, v45
	v_mul_f32_e32 v46, v84, v46
	v_mul_f32_e32 v47, v84, v41
	v_cvt_pk_bf16_f32 v41, v46, v47
	v_mul_f32_e32 v152, v84, v152
	v_mul_f32_e32 v153, v84, v42
	v_cvt_pk_bf16_f32 v42, v152, v153
	v_lshlrev_b32_e32 v154, 16, v43
	v_and_b32_e32 v43, 0xffff0000, v43
	v_mul_f32_e32 v154, v84, v154
	v_mul_f32_e32 v84, v84, v43
	v_cvt_pk_bf16_f32 v43, v154, v84
	ds_write_b128 v134, v[40:43]
	s_waitcnt vmcnt(9)
	v_lshlrev_b32_e32 v40, 16, v36
	v_and_b32_e32 v36, 0xffff0000, v36
	v_lshlrev_b32_e32 v42, 16, v37
	v_and_b32_e32 v37, 0xffff0000, v37
	v_lshlrev_b32_e32 v155, 16, v38
	v_and_b32_e32 v38, 0xffff0000, v38
	v_mul_f32_e32 v40, v88, v40
	v_mul_f32_e32 v41, v88, v36
	v_cvt_pk_bf16_f32 v36, v40, v41
	v_mul_f32_e32 v42, v88, v42
	v_mul_f32_e32 v43, v88, v37
	v_cvt_pk_bf16_f32 v37, v42, v43
	v_mul_f32_e32 v155, v88, v155
	v_mul_f32_e32 v156, v88, v38
	v_cvt_pk_bf16_f32 v38, v155, v156
	v_lshlrev_b32_e32 v157, 16, v39
	v_and_b32_e32 v39, 0xffff0000, v39
	v_mul_f32_e32 v157, v88, v157
	v_mul_f32_e32 v88, v88, v39
	v_cvt_pk_bf16_f32 v39, v157, v88
	ds_write_b128 v135, v[36:39]
	s_waitcnt vmcnt(7)
	v_lshlrev_b32_e32 v36, 16, v32
	v_and_b32_e32 v32, 0xffff0000, v32
	v_lshlrev_b32_e32 v38, 16, v33
	v_and_b32_e32 v33, 0xffff0000, v33
	v_lshlrev_b32_e32 v158, 16, v34
	v_and_b32_e32 v34, 0xffff0000, v34
	v_mul_f32_e32 v36, v89, v36
	v_mul_f32_e32 v37, v89, v32
	v_cvt_pk_bf16_f32 v32, v36, v37
	v_mul_f32_e32 v38, v89, v38
	v_mul_f32_e32 v39, v89, v33
	v_cvt_pk_bf16_f32 v33, v38, v39
	v_mul_f32_e32 v158, v89, v158
	v_mul_f32_e32 v159, v89, v34
	v_cvt_pk_bf16_f32 v34, v158, v159
	v_lshlrev_b32_e32 v160, 16, v35
	v_and_b32_e32 v35, 0xffff0000, v35
	v_mul_f32_e32 v160, v89, v160
	v_mul_f32_e32 v89, v89, v35
	v_cvt_pk_bf16_f32 v35, v160, v89
	ds_write_b128 v136, v[32:35]
	v_cvt_pk_bf16_f32 v32, v90, v44
	v_cvt_pk_bf16_f32 v33, v40, v36
	v_add_u32_e32 v34, v102, v123
	ds_write_b64 v34, v[32:33]
	v_cvt_pk_bf16_f32 v32, v91, v45
	v_cvt_pk_bf16_f32 v33, v41, v37
	v_add_u32_e32 v34, v102, v124
	ds_write_b64 v34, v[32:33]
	s_waitcnt vmcnt(4)
	v_lshlrev_b32_e32 v32, 16, v4
	v_lshlrev_b32_e32 v33, 16, v16
	v_and_or_b32 v32, v0, s95, v32
	v_and_or_b32 v33, v8, s95, v33
	v_add_u32_e32 v34, v103, v123
	v_lshrrev_b32_e32 v0, 16, v0
	ds_write_b64 v34, v[32:33] offset:32768
	v_and_or_b32 v32, v4, s94, v0
	v_lshrrev_b32_e32 v0, 16, v8
	v_and_or_b32 v33, v16, s94, v0
	v_add_u32_e32 v0, v103, v124
	ds_write_b64 v0, v[32:33] offset:32768
	v_add_u32_e32 v0, v102, v125
	v_cvt_pk_bf16_f32 v32, v92, v46
	v_cvt_pk_bf16_f32 v33, v42, v38
	ds_write_b64 v0, v[32:33]
	v_add_u32_e32 v0, v102, v126
	v_cvt_pk_bf16_f32 v32, v93, v47
	v_cvt_pk_bf16_f32 v33, v43, v39
	ds_write_b64 v0, v[32:33]
	v_lshlrev_b32_e32 v0, 16, v5
	v_and_or_b32 v32, v1, s95, v0
	v_lshlrev_b32_e32 v0, 16, v17
	v_and_or_b32 v33, v9, s95, v0
	v_add_u32_e32 v0, v103, v125
	ds_write_b64 v0, v[32:33] offset:32768
	v_lshrrev_b32_e32 v0, 16, v1
	v_lshrrev_b32_e32 v1, 16, v9
	v_and_or_b32 v0, v5, s94, v0
	v_and_or_b32 v1, v17, s94, v1
	v_add_u32_e32 v4, v103, v126
	ds_write_b64 v4, v[0:1] offset:32768
	v_cvt_pk_bf16_f32 v0, v94, v152
	v_cvt_pk_bf16_f32 v1, v155, v158
	v_add_u32_e32 v4, v102, v127
	ds_write_b64 v4, v[0:1]
	v_cvt_pk_bf16_f32 v0, v95, v153
	v_cvt_pk_bf16_f32 v1, v156, v159
	v_add_u32_e32 v4, v102, v128
	ds_write_b64 v4, v[0:1]
	v_lshlrev_b32_e32 v0, 16, v6
	v_lshlrev_b32_e32 v1, 16, v18
	v_and_or_b32 v0, v2, s95, v0
	v_and_or_b32 v1, v10, s95, v1
	v_add_u32_e32 v4, v103, v127
	ds_write_b64 v4, v[0:1] offset:32768
	v_lshrrev_b32_e32 v0, 16, v2
	v_lshrrev_b32_e32 v1, 16, v10
	v_and_or_b32 v0, v6, s94, v0
	v_and_or_b32 v1, v18, s94, v1
	v_add_u32_e32 v2, v103, v128
	ds_write_b64 v2, v[0:1] offset:32768
	v_cvt_pk_bf16_f32 v0, v151, v154
	v_cvt_pk_bf16_f32 v1, v157, v160
	v_add_u32_e32 v2, v102, v129
	ds_write_b64 v2, v[0:1]
	v_cvt_pk_bf16_f32 v0, v67, v84
	v_cvt_pk_bf16_f32 v1, v88, v89
	v_add_u32_e32 v2, v102, v130
	ds_write_b64 v2, v[0:1]
	v_lshlrev_b32_e32 v0, 16, v7
	v_lshlrev_b32_e32 v1, 16, v19
	v_and_or_b32 v0, v3, s95, v0
	v_and_or_b32 v1, v11, s95, v1
	v_add_u32_e32 v2, v103, v129
	ds_write_b64 v2, v[0:1] offset:32768
	v_lshrrev_b32_e32 v0, 16, v3
	v_lshrrev_b32_e32 v1, 16, v11
	v_and_or_b32 v0, v7, s94, v0
	v_and_or_b32 v1, v19, s94, v1
	v_add_u32_e32 v2, v103, v130
	s_lshl_b32 s0, vcc_lo, 7
	ds_write_b64 v2, v[0:1] offset:32768
	v_or_b32_e32 v0, s0, v85
	v_mul_lo_u32 v0, v0, s3
	v_add_u32_e32 v4, s33, v0
	v_ashrrev_i32_e32 v5, 31, v4
	v_lshlrev_b64 v[0:1], 10, v[4:5]
	v_add_u32_e32 v8, s3, v4
	v_lshl_add_u64 v[0:1], v[64:65], 0, v[0:1]
	v_ashrrev_i32_e32 v9, 31, v8
	s_waitcnt lgkmcnt(0)
	s_barrier
; #define SCAN_LOAD(j) do { \
;         _Pragma("unroll") for (int i = 0; i < 4; ++i) { const size_t r = (size_t)(rfirst + rstep * ((j) * 128 + sp * 4 + i)); \
;             kreg[i] = *(const u32x4*)(K0 + r * 512 + h * 128 + ch * 8); vreg[i] = *(const u32x4*)(P0 + r * LDP + 1536 + h * 128 + ch * 8); } \
;         } while (0)
; template <int SPLIT> __device__ __forceinline__ void scan_item(const Params& p, unsigned char* smem, const int item, const int vh) {
;     ...
;             SCAN_LOAD(jn);
;             __builtin_amdgcn_sched_barrier(0);
;             const int l = wid * 16 + li;
;             const float Ml = M_s[l], gl = g_s[l];
;             f32x4 acc[8];
; #pragma unroll
;             for (int nb = 0; nb < 8; ++nb) acc[nb] = (f32x4){0.f, 0.f, 0.f, 0.f};
;             mm16<8>(acc, KP, qf, lane);
	global_load_dwordx4 v[44:47], v[0:1], off
	v_mad_i64_i32 v[0:1], s[4:5], v4, s88, v[80:81]
	v_lshlrev_b64 v[4:5], 10, v[8:9]
	v_add_u32_e32 v16, s3, v8
	v_lshl_add_u64 v[4:5], v[64:65], 0, v[4:5]
	v_ashrrev_i32_e32 v17, 31, v16
	global_load_dwordx4 v[40:43], v[4:5], off
	v_mad_i64_i32 v[4:5], s[4:5], v8, s88, v[80:81]
	v_lshlrev_b64 v[8:9], 10, v[16:17]
	v_lshl_add_u64 v[8:9], v[64:65], 0, v[8:9]
	global_load_dwordx4 v[36:39], v[8:9], off
	v_mad_i64_i32 v[8:9], s[4:5], v16, s88, v[80:81]
	v_add_u32_e32 v16, s3, v16
	v_ashrrev_i32_e32 v17, 31, v16
	v_lshlrev_b64 v[18:19], 10, v[16:17]
	v_lshl_add_u64 v[18:19], v[64:65], 0, v[18:19]
	v_mad_i64_i32 v[16:17], s[4:5], v16, s88, v[80:81]
	global_load_dwordx4 v[0:3], v[0:1], off offset:3072
	v_sub_f32_e32 v67, v86, v87
	global_load_dwordx4 v[4:7], v[4:5], off offset:3072
	v_mul_f32_e32 v67, 0x3fb8aa3b, v67
	global_load_dwordx4 v[8:11], v[8:9], off offset:3072
	v_exp_f32_e32 v84, v67
	global_load_dwordx4 v[32:35], v[18:19], off
	s_nop 0
	global_load_dwordx4 v[16:19], v[16:17], off offset:3072
	v_add_u32_e32 v67, 0, v107
	ds_read_b128 v[88:91], v67
	ds_read_b128 v[92:95], v67 offset:4096
	ds_read_b32 v151, v105
	ds_read_b128 v[152:155], v67 offset:8192
	ds_read_b128 v[156:159], v67 offset:12288
	ds_read_b32 v171, v104
	s_waitcnt vmcnt(11) lgkmcnt(5)
	v_mfma_f32_16x16x32_bf16 v[88:91], v[88:91], v[28:31], 0
	s_waitcnt lgkmcnt(4)
	v_mfma_f32_16x16x32_bf16 v[92:95], v[92:95], v[28:31], 0
	s_waitcnt lgkmcnt(2)
	v_mfma_f32_16x16x32_bf16 v[152:155], v[152:155], v[28:31], 0
	s_waitcnt lgkmcnt(1)
	v_mfma_f32_16x16x32_bf16 v[156:159], v[156:159], v[28:31], 0
	ds_read_b128 v[160:163], v67 offset:16384
	ds_read_b128 v[164:167], v67 offset:20480
	ds_read_b128 v[172:175], v67 offset:24576
	ds_read_b128 v[178:181], v67 offset:28672
	s_waitcnt lgkmcnt(3)
	v_mfma_f32_16x16x32_bf16 v[160:163], v[160:163], v[28:31], 0
	s_waitcnt lgkmcnt(2)
	v_mfma_f32_16x16x32_bf16 v[164:167], v[164:167], v[28:31], 0
	s_waitcnt lgkmcnt(1)
	v_mfma_f32_16x16x32_bf16 v[172:175], v[172:175], v[28:31], 0
	s_waitcnt lgkmcnt(0)
	v_mfma_f32_16x16x32_bf16 v[178:181], v[178:181], v[28:31], 0
	v_add_u32_e32 v67, 0, v109
	ds_read_b128 v[218:221], v67
	ds_read_b128 v[222:225], v67 offset:4096
	ds_read_b128 v[226:229], v67 offset:8192
	ds_read_b128 v[230:233], v67 offset:12288
	ds_read_b128 v[234:237], v67 offset:16384
	ds_read_b128 v[182:185], v67 offset:20480
	s_waitcnt vmcnt(10) lgkmcnt(5)
	v_mfma_f32_16x16x32_bf16 v[88:91], v[218:221], v[24:27], v[88:91]
	ds_read_b128 v[218:221], v67 offset:24576
	s_waitcnt lgkmcnt(5)
	v_mfma_f32_16x16x32_bf16 v[92:95], v[222:225], v[24:27], v[92:95]
	ds_read_b128 v[222:225], v67 offset:28672
	s_waitcnt lgkmcnt(5)
	v_mfma_f32_16x16x32_bf16 v[152:155], v[226:229], v[24:27], v[152:155]
	v_add_u32_e32 v67, 0, v111
	ds_read_b128 v[226:229], v67
	s_waitcnt lgkmcnt(5)
	v_mfma_f32_16x16x32_bf16 v[156:159], v[230:233], v[24:27], v[156:159]
	ds_read_b128 v[230:233], v67 offset:4096
	s_waitcnt lgkmcnt(5)
	v_mfma_f32_16x16x32_bf16 v[160:163], v[234:237], v[24:27], v[160:163]
	ds_read_b128 v[234:237], v67 offset:8192
	s_waitcnt lgkmcnt(5)
	v_mfma_f32_16x16x32_bf16 v[164:167], v[182:185], v[24:27], v[164:167]
	ds_read_b128 v[182:185], v67 offset:12288
	s_waitcnt lgkmcnt(5)
	v_mfma_f32_16x16x32_bf16 v[172:175], v[218:221], v[24:27], v[172:175]
	ds_read_b128 v[218:221], v67 offset:16384
	s_waitcnt lgkmcnt(5)
	v_mfma_f32_16x16x32_bf16 v[178:181], v[222:225], v[24:27], v[178:181]
	ds_read_b128 v[222:225], v67 offset:20480
	s_waitcnt vmcnt(9) lgkmcnt(5)
	v_mfma_f32_16x16x32_bf16 v[88:91], v[226:229], v[20:23], v[88:91]
	ds_read_b128 v[226:229], v67 offset:24576
	s_waitcnt lgkmcnt(5)
	v_mfma_f32_16x16x32_bf16 v[92:95], v[230:233], v[20:23], v[92:95]
	ds_read_b128 v[230:233], v67 offset:28672
	s_waitcnt lgkmcnt(5)
	v_mfma_f32_16x16x32_bf16 v[152:155], v[234:237], v[20:23], v[152:155]
	v_add_u32_e32 v67, 0, v113
	ds_read_b128 v[234:237], v67
	s_waitcnt lgkmcnt(5)
	v_mfma_f32_16x16x32_bf16 v[156:159], v[182:185], v[20:23], v[156:159]
	ds_read_b128 v[182:185], v67 offset:4096
	s_waitcnt lgkmcnt(5)
	v_mfma_f32_16x16x32_bf16 v[160:163], v[218:221], v[20:23], v[160:163]
	ds_read_b128 v[218:221], v67 offset:8192
	s_waitcnt lgkmcnt(5)
	v_mfma_f32_16x16x32_bf16 v[164:167], v[222:225], v[20:23], v[164:167]
	ds_read_b128 v[222:225], v67 offset:12288
	s_waitcnt lgkmcnt(5)
	v_mfma_f32_16x16x32_bf16 v[172:175], v[226:229], v[20:23], v[172:175]
	ds_read_b128 v[226:229], v67 offset:16384
	s_waitcnt lgkmcnt(5)
	v_mfma_f32_16x16x32_bf16 v[178:181], v[230:233], v[20:23], v[178:181]
	ds_read_b128 v[230:233], v67 offset:20480
	s_waitcnt vmcnt(8) lgkmcnt(5)
	v_mfma_f32_16x16x32_bf16 v[88:91], v[234:237], v[12:15], v[88:91]
	ds_read_b128 v[234:237], v67 offset:24576
	s_waitcnt lgkmcnt(5)
	v_mfma_f32_16x16x32_bf16 v[92:95], v[182:185], v[12:15], v[92:95]
	ds_read_b128 v[182:185], v67 offset:28672
	s_waitcnt lgkmcnt(5)
	v_mfma_f32_16x16x32_bf16 v[152:155], v[218:221], v[12:15], v[152:155]
	s_nop 0
	s_waitcnt lgkmcnt(4)
	v_mfma_f32_16x16x32_bf16 v[156:159], v[222:225], v[12:15], v[156:159]
	s_nop 0
	s_waitcnt lgkmcnt(3)
	v_mfma_f32_16x16x32_bf16 v[160:163], v[226:229], v[12:15], v[160:163]
	s_nop 0
	s_waitcnt lgkmcnt(2)
	v_mfma_f32_16x16x32_bf16 v[164:167], v[230:233], v[12:15], v[164:167]
	s_nop 0
	s_waitcnt lgkmcnt(1)
	v_mfma_f32_16x16x32_bf16 v[172:175], v[234:237], v[12:15], v[172:175]
	s_nop 0
	s_waitcnt lgkmcnt(0)
	v_mfma_f32_16x16x32_bf16 v[178:181], v[182:185], v[12:15], v[178:181]
	s_nop 0
	v_mov_b32_e32 v67, s6
	ds_read_b32 v67, v67
	s_waitcnt lgkmcnt(0)
; __device__ __forceinline__ unsigned cvt_pk(float lo, float hi) { unsigned r; asm volatile("v_cvt_pk_bf16_f32 %0, %1, %2" : "=v"(r) : "v"(lo), "v"(hi)); return r; }
; __device__ __forceinline__ float bflo(unsigned w) { return __uint_as_float(w << 16); }
; __device__ __forceinline__ float bfhi(unsigned w) { return __uint_as_float(w & 0xffff0000u); }
; template <int SPLIT> __device__ __forceinline__ void scan_item(const Params& p, unsigned char* smem, const int item, const int vh) {
;     ...
;             const float rowf = __expf(fminf(sc[1] - Ml, 80.f));
; #pragma unroll
;             for (int nb = 0; nb < 8; ++nb) { float pv[4];
; #pragma unroll
;                 for (int jj = 0; jj < 4; ++jj) { const int s = nb * 16 + kq * 4 + jj; pv[jj] = (s <= l) ? acc[nb][jj] * rowf : 0.f; rs += pv[jj]; }
;                 pp[nb].x = cvt_pk(pv[0], pv[1]); pp[nb].y = cvt_pk(pv[2], pv[3]); }
;             __builtin_amdgcn_sched_barrier(0);
;             float nq = 0.f;
; #pragma unroll
;             for (int ks = 0; ks < 4; ++ks) { const f32x4 n0 = *(const f32x4*)(n_s + ks * 32 + kq * 8), n1 = *(const f32x4*)(n_s + ks * 32 + kq * 8 + 4);
;                 const u32x4 qw = *(const u32x4*)&qf[ks];
;                 nq += bflo(qw.x) * n0[0] + bfhi(qw.x) * n0[1] + bflo(qw.y) * n0[2] + bfhi(qw.y) * n0[3] + bflo(qw.z) * n1[0] + bfhi(qw.z) * n1[1] + bflo(qw.w) * n1[2] + bfhi(qw.w) * n1[3]; }
	v_sub_f32_e32 v67, v67, v171
	v_min_f32_e32 v67, 0x42a00000, v67
	v_mul_f32_e32 v67, 0x3fb8aa3b, v67
	v_exp_f32_e32 v87, v67
	s_nop 0
	v_mul_f32_e32 v67, v88, v87
	v_mul_f32_e32 v88, v89, v87
	v_cndmask_b32_e64 v67, v67, 0, s[10:11]
	v_mul_f32_e32 v89, v90, v87
	v_mul_f32_e32 v90, v91, v87
	v_cndmask_b32_e64 v91, 0, v88, s[12:13]
	v_add_f32_e32 v168, 0, v67
	v_cndmask_b32_e64 v89, v89, 0, s[14:15]
	v_cvt_pk_bf16_f32 v88, v67, v91
	v_add_f32_e32 v67, v91, v168
	v_cndmask_b32_e64 v90, v90, 0, s[16:17]
	v_add_f32_e32 v67, v89, v67
	v_add_f32_e32 v67, v90, v67
	v_cvt_pk_bf16_f32 v89, v89, v90
	v_mul_f32_e32 v90, v92, v87
	v_cndmask_b32_e64 v90, v90, 0, s[18:19]
	v_mul_f32_e32 v91, v93, v87
	v_add_f32_e32 v67, v90, v67
	v_cndmask_b32_e64 v91, v91, 0, s[20:21]
	v_mul_f32_e32 v92, v94, v87
	v_add_f32_e32 v67, v91, v67
	v_cndmask_b32_e64 v92, v92, 0, s[22:23]
	v_mul_f32_e32 v93, v95, v87
	v_add_f32_e32 v67, v92, v67
	v_cndmask_b32_e64 v93, v93, 0, s[24:25]
	v_cvt_pk_bf16_f32 v90, v90, v91
	v_cvt_pk_bf16_f32 v91, v92, v93
	v_mul_f32_e32 v92, v152, v87
	v_add_f32_e32 v67, v93, v67
	v_cndmask_b32_e64 v92, v92, 0, s[26:27]
	v_mul_f32_e32 v93, v153, v87
	v_add_f32_e32 v67, v92, v67
	v_cndmask_b32_e64 v93, v93, 0, s[28:29]
	v_mul_f32_e32 v94, v154, v87
	v_add_f32_e32 v67, v93, v67
	v_cndmask_b32_e64 v94, v94, 0, s[30:31]
	v_mul_f32_e32 v95, v155, v87
	v_add_f32_e32 v67, v94, v67
	v_cndmask_b32_e64 v95, v95, 0, s[34:35]
	v_cvt_pk_bf16_f32 v92, v92, v93
	v_cvt_pk_bf16_f32 v93, v94, v95
	v_mul_f32_e32 v94, v156, v87
	v_add_f32_e32 v67, v95, v67
	v_cndmask_b32_e64 v94, v94, 0, s[36:37]
	v_mul_f32_e32 v95, v157, v87
	v_add_f32_e32 v67, v94, v67
	v_cndmask_b32_e64 v95, v95, 0, s[38:39]
	v_mul_f32_e32 v152, v158, v87
	v_add_f32_e32 v67, v95, v67
	v_cndmask_b32_e64 v152, v152, 0, s[40:41]
	v_mul_f32_e32 v153, v159, v87
	v_add_f32_e32 v67, v152, v67
	v_cndmask_b32_e64 v153, v153, 0, s[42:43]
	v_cvt_pk_bf16_f32 v94, v94, v95
	v_cvt_pk_bf16_f32 v95, v152, v153
	v_mul_f32_e32 v152, v160, v87
	v_add_f32_e32 v67, v153, v67
	v_cndmask_b32_e64 v152, v152, 0, s[44:45]
	v_mul_f32_e32 v153, v161, v87
	v_add_f32_e32 v67, v152, v67
	v_cndmask_b32_e64 v153, v153, 0, s[46:47]
	v_mul_f32_e32 v154, v162, v87
	v_add_f32_e32 v67, v153, v67
	v_cndmask_b32_e64 v154, v154, 0, s[48:49]
	v_mul_f32_e32 v155, v163, v87
	v_add_f32_e32 v67, v154, v67
	v_cndmask_b32_e64 v155, v155, 0, s[50:51]
	v_cvt_pk_bf16_f32 v168, v152, v153
	v_mul_f32_e32 v152, v164, v87
	v_add_f32_e32 v67, v155, v67
	v_cndmask_b32_e64 v152, v152, 0, s[52:53]
	v_add_f32_e32 v161, v152, v67
	v_mul_f32_e32 v67, v165, v87
	v_cndmask_b32_e64 v163, v67, 0, s[54:55]
	v_mul_f32_e32 v67, v166, v87
	v_cndmask_b32_e64 v183, v67, 0, s[56:57]
	v_mul_f32_e32 v67, v167, v87
	v_cndmask_b32_e64 v185, v67, 0, s[58:59]
	v_mul_f32_e32 v67, v172, v87
	v_cndmask_b32_e64 v189, v67, 0, s[60:61]
	v_mul_f32_e32 v67, v173, v87
	v_cndmask_b32_e64 v173, v67, 0, s[62:63]
	v_mul_f32_e32 v67, v174, v87
	v_cndmask_b32_e64 v191, v67, 0, s[64:65]
	v_mul_f32_e32 v67, v175, v87
	v_cvt_pk_bf16_f32 v169, v154, v155
	v_cvt_pk_bf16_f32 v186, v152, v163
	v_cndmask_b32_e64 v175, v67, 0, s[66:67]
	v_mul_f32_e32 v67, v178, v87
	v_mul_f32_e32 v152, v179, v87
	v_cndmask_b32_e64 v67, v67, 0, s[68:69]
	v_cndmask_b32_e64 v177, v152, 0, s[70:71]
	v_mul_f32_e32 v152, v180, v87
	v_mul_f32_e32 v87, v181, v87
	v_cvt_pk_bf16_f32 v187, v183, v185
	v_cvt_pk_bf16_f32 v192, v189, v173
	v_cvt_pk_bf16_f32 v193, v191, v175
	v_cndmask_b32_e64 v200, v152, 0, s[72:73]
	v_cndmask_b32_e64 v201, v87, 0, s[74:75]
	v_cvt_pk_bf16_f32 v178, v67, v177
	v_cvt_pk_bf16_f32 v179, v200, v201
	ds_read_b128 v[152:155], v137
	ds_read_b128 v[156:159], v137 offset:16
	v_lshlrev_b32_e32 v87, 16, v28
	v_and_b32_e32 v160, 0xffff0000, v28
	v_and_b32_e32 v195, 0xffff0000, v27
	s_waitcnt lgkmcnt(1)
	v_mul_f32_e32 v162, v152, v87
	v_lshlrev_b32_e32 v87, 16, v29
	v_mul_f32_e32 v182, v154, v87
	v_and_b32_e32 v87, 0xffff0000, v29
	v_mul_f32_e32 v160, v153, v160
	v_mul_f32_e32 v184, v155, v87
	v_lshlrev_b32_e32 v87, 16, v30
	ds_read_b128 v[152:155], v137 offset:128
	s_waitcnt lgkmcnt(1)
	v_mul_f32_e32 v188, v156, v87
	v_and_b32_e32 v87, 0xffff0000, v30
	v_mul_f32_e32 v172, v157, v87
	v_lshlrev_b32_e32 v87, 16, v31
	v_mul_f32_e32 v190, v158, v87
	v_and_b32_e32 v87, 0xffff0000, v31
	v_pk_add_f32 v[180:181], v[162:163], v[160:161]
	v_mul_f32_e32 v174, v159, v87
	ds_read_b128 v[156:159], v137 offset:144
	v_and_b32_e32 v161, 0xffff0000, v24
	v_lshlrev_b32_e32 v160, 16, v24
	s_waitcnt lgkmcnt(1)
	v_mul_f32_e32 v162, v153, v161
	v_pk_fma_f32 v[152:153], v[152:153], v[160:161], v[162:163] op_sel_hi:[1,1,0]
	v_and_b32_e32 v161, 0xffff0000, v25
	v_lshlrev_b32_e32 v160, 16, v25
	v_pk_fma_f32 v[152:153], v[154:155], v[160:161], v[152:153]
	v_mul_f32_e32 v154, v155, v161
	v_pk_add_f32 v[152:153], v[154:155], v[152:153] op_sel_hi:[0,1]
	v_and_b32_e32 v155, 0xffff0000, v26
	v_lshlrev_b32_e32 v154, 16, v26
	s_waitcnt lgkmcnt(0)
	v_pk_fma_f32 v[152:153], v[156:157], v[154:155], v[152:153]
	v_mul_f32_e32 v154, v157, v155
	v_pk_add_f32 v[156:157], v[154:155], v[152:153] op_sel_hi:[0,1]
	ds_read_b128 v[152:155], v137 offset:256
	ds_read_b128 v[160:163], v137 offset:272
	v_lshlrev_b32_e32 v194, 16, v27
	v_and_b32_e32 v165, 0xffff0000, v20
	v_pk_fma_f32 v[156:157], v[158:159], v[194:195], v[156:157]
	v_lshlrev_b32_e32 v164, 16, v20
	s_waitcnt lgkmcnt(1)
	v_mul_f32_e32 v158, v153, v165
	v_pk_fma_f32 v[152:153], v[152:153], v[164:165], v[158:159] op_sel_hi:[1,1,0]
	v_and_b32_e32 v165, 0xffff0000, v21
	v_lshlrev_b32_e32 v164, 16, v21
	v_pk_fma_f32 v[152:153], v[154:155], v[164:165], v[152:153]
	v_mul_f32_e32 v154, v155, v165
	v_pk_add_f32 v[152:153], v[154:155], v[152:153] op_sel_hi:[0,1]
	v_and_b32_e32 v155, 0xffff0000, v22
	v_lshlrev_b32_e32 v154, 16, v22
	s_waitcnt lgkmcnt(0)
; template <int SPLIT> __device__ __forceinline__ void scan_item(const Params& p, unsigned char* smem, const int item, const int vh) {
;     ...
;             rs += __shfl_xor(rs, 16); rs += __shfl_xor(rs, 32); nq += __shfl_xor(nq, 16); nq += __shfl_xor(nq, 32);
;             const float exl = __expf(m_old - Ml);
;             const float den = rs + exl * nq;
;             const float hinv = __builtin_amdgcn_rcpf(fmaxf(fabsf(den), __expf(-(gl + Ml))));
;             __syncthreads();
; #pragma unroll
;             for (int nb = 0; nb < 8; ++nb) *(u32x2*)(KP + swz(l, nb * 2 + (kq >> 1)) + (kq & 1) * 8) = pp[nb];
;             f32x4 acc2[NBV];
; #pragma unroll
;             for (int nb = 0; nb < NBV; ++nb) acc2[nb] = (f32x4){0.f, 0.f, 0.f, 0.f};
;             __builtin_amdgcn_sched_barrier(0);
;             mm16<NBV>(acc2, CS + vh * 16384, qf, lane);
	v_pk_fma_f32 v[152:153], v[160:161], v[154:155], v[152:153]
	v_mul_f32_e32 v154, v161, v155
	v_pk_add_f32 v[160:161], v[154:155], v[152:153] op_sel_hi:[0,1]
	ds_read_b128 v[152:155], v137 offset:384
	ds_read_b128 v[164:167], v137 offset:400
	v_and_b32_e32 v199, 0xffff0000, v12
	v_lshlrev_b32_e32 v198, 16, v12
	v_and_b32_e32 v197, 0xffff0000, v23
	s_waitcnt lgkmcnt(1)
	v_mul_f32_e32 v158, v153, v199
	v_pk_fma_f32 v[152:153], v[152:153], v[198:199], v[158:159] op_sel_hi:[1,1,0]
	v_and_b32_e32 v199, 0xffff0000, v13
	v_lshlrev_b32_e32 v198, 16, v13
	v_pk_fma_f32 v[152:153], v[154:155], v[198:199], v[152:153]
	v_mul_f32_e32 v154, v155, v199
	v_pk_add_f32 v[152:153], v[154:155], v[152:153] op_sel_hi:[0,1]
	v_and_b32_e32 v155, 0xffff0000, v14
	v_lshlrev_b32_e32 v154, 16, v14
	s_waitcnt lgkmcnt(0)
	v_pk_fma_f32 v[152:153], v[164:165], v[154:155], v[152:153]
	v_mul_f32_e32 v154, v165, v155
	v_pk_add_f32 v[164:165], v[182:183], v[180:181]
	v_pk_add_f32 v[152:153], v[154:155], v[152:153] op_sel_hi:[0,1]
	v_pk_add_f32 v[164:165], v[184:185], v[164:165]
	v_and_b32_e32 v155, 0xffff0000, v15
	v_lshlrev_b32_e32 v154, 16, v15
	v_pk_add_f32 v[164:165], v[188:189], v[164:165]
	v_lshlrev_b32_e32 v196, 16, v23
	v_pk_fma_f32 v[152:153], v[166:167], v[154:155], v[152:153]
	v_and_b32_e32 v154, 64, v150
	v_pk_add_f32 v[164:165], v[172:173], v[164:165]
	v_pk_fma_f32 v[160:161], v[162:163], v[196:197], v[160:161]
	v_add_u32_e32 v162, 64, v154
	v_pk_add_f32 v[164:165], v[190:191], v[164:165]
	v_mul_f32_e32 v154, v159, v195
	v_pk_add_f32 v[164:165], v[174:175], v[164:165]
	v_pk_add_f32 v[156:157], v[154:155], v[156:157] op_sel_hi:[0,1]
	v_mul_f32_e32 v154, v163, v197
	v_xor_b32_e32 v87, 16, v150
	v_pk_add_f32 v[164:165], v[66:67], v[164:165]
	v_mov_b32_e32 v157, v177
	v_pk_add_f32 v[158:159], v[154:155], v[160:161] op_sel_hi:[0,1]
	v_mul_f32_e32 v154, v167, v155
	v_cmp_lt_i32_e32 vcc, v87, v162
	v_pk_add_f32 v[156:157], v[156:157], v[164:165]
	v_mov_b32_e32 v159, v200
	v_pk_add_f32 v[152:153], v[154:155], v[152:153] op_sel_hi:[0,1]
	v_cndmask_b32_e32 v87, v150, v87, vcc
	v_pk_add_f32 v[156:157], v[158:159], v[156:157]
	v_mov_b32_e32 v153, v201
	v_lshlrev_b32_e32 v87, 2, v87
	v_pk_add_f32 v[152:153], v[152:153], v[156:157]
	ds_bpermute_b32 v155, v87, v153
	ds_bpermute_b32 v154, v87, v152
	v_xor_b32_e32 v67, 32, v150
	v_cmp_lt_i32_e32 vcc, v67, v162
	v_sub_f32_e32 v86, v86, v171
	v_mul_f32_e32 v86, 0x3fb8aa3b, v86
	v_cndmask_b32_e32 v67, v150, v67, vcc
	v_lshlrev_b32_e32 v67, 2, v67
	s_waitcnt lgkmcnt(0)
	v_pk_add_f32 v[152:153], v[152:153], v[154:155]
	ds_bpermute_b32 v155, v67, v153
	ds_bpermute_b32 v154, v67, v152
	v_add_f32_e32 v151, v171, v151
	v_exp_f32_e32 v86, v86
	v_mul_f32_e32 v151, 0xbfb8aa3b, v151
	v_exp_f32_e32 v151, v151
	s_waitcnt lgkmcnt(0)
	v_pk_add_f32 v[152:153], v[152:153], v[154:155]
	s_nop 0
	v_fmac_f32_e32 v153, v86, v152
	v_max_f32_e64 v151, |v153|, v151
	s_barrier
	ds_write_b64 v138, v[88:89]
	ds_write_b64 v139, v[90:91]
	ds_write_b64 v140, v[92:93]
	ds_write_b64 v141, v[94:95]
	ds_write_b64 v142, v[168:169]
	ds_write_b64 v143, v[186:187]
	ds_write_b64 v144, v[192:193]
	ds_write_b64 v145, v[178:179]
	v_add_u32_e32 v156, s89, v107
	ds_read_b128 v[88:91], v156
	ds_read_b128 v[92:95], v156 offset:4096
	ds_read_b128 v[152:155], v156 offset:8192
	ds_read_b128 v[156:159], v156 offset:12288
	s_waitcnt lgkmcnt(3)
	v_mfma_f32_16x16x32_bf16 v[88:91], v[88:91], v[28:31], 0
	s_waitcnt lgkmcnt(2)
	v_mfma_f32_16x16x32_bf16 v[92:95], v[92:95], v[28:31], 0
	s_waitcnt lgkmcnt(1)
	v_mfma_f32_16x16x32_bf16 v[152:155], v[152:155], v[28:31], 0
	s_waitcnt lgkmcnt(0)
	v_mfma_f32_16x16x32_bf16 v[28:31], v[156:159], v[28:31], 0
	v_add_u32_e32 v160, s89, v109
	ds_read_b128 v[226:229], v160
	ds_read_b128 v[230:233], v160 offset:4096
	ds_read_b128 v[234:237], v160 offset:8192
	ds_read_b128 v[156:159], v160 offset:12288
	s_waitcnt lgkmcnt(3)
	v_mfma_f32_16x16x32_bf16 v[88:91], v[226:229], v[24:27], v[88:91]
	s_nop 0
	s_waitcnt lgkmcnt(2)
	v_mfma_f32_16x16x32_bf16 v[92:95], v[230:233], v[24:27], v[92:95]
	s_nop 0
	s_waitcnt lgkmcnt(1)
	v_mfma_f32_16x16x32_bf16 v[152:155], v[234:237], v[24:27], v[152:155]
	s_nop 0
	s_waitcnt lgkmcnt(0)
	v_mfma_f32_16x16x32_bf16 v[24:27], v[156:159], v[24:27], v[28:31]
	s_nop 0
	v_add_u32_e32 v156, s89, v111
	s_nop 1
	ds_read_b128 v[28:31], v156
	s_waitcnt lgkmcnt(0)
	v_mfma_f32_16x16x32_bf16 v[28:31], v[28:31], v[20:23], v[88:91]
	s_nop 2
	ds_read_b128 v[88:91], v156 offset:4096
	s_waitcnt lgkmcnt(0)
	v_mfma_f32_16x16x32_bf16 v[88:91], v[88:91], v[20:23], v[92:95]
	s_nop 2
	ds_read_b128 v[92:95], v156 offset:8192
	s_waitcnt lgkmcnt(0)
	v_mfma_f32_16x16x32_bf16 v[92:95], v[92:95], v[20:23], v[152:155]
	s_nop 2
	ds_read_b128 v[152:155], v156 offset:12288
	s_waitcnt lgkmcnt(0)
	v_mfma_f32_16x16x32_bf16 v[20:23], v[152:155], v[20:23], v[24:27]
	v_add_u32_e32 v156, s89, v113
	s_nop 1
	ds_read_b128 v[226:229], v156
	ds_read_b128 v[230:233], v156 offset:4096
	ds_read_b128 v[234:237], v156 offset:8192
	ds_read_b128 v[24:27], v156 offset:12288
	s_waitcnt lgkmcnt(3)
	v_mfma_f32_16x16x32_bf16 v[152:155], v[226:229], v[12:15], v[28:31]
	s_nop 0
	s_waitcnt lgkmcnt(2)
	v_mfma_f32_16x16x32_bf16 v[88:91], v[230:233], v[12:15], v[88:91]
	s_nop 0
	s_waitcnt lgkmcnt(1)
	v_mfma_f32_16x16x32_bf16 v[92:95], v[234:237], v[12:15], v[92:95]
	s_nop 0
	s_waitcnt lgkmcnt(0)
; __device__ __forceinline__ unsigned cvt_pk(float lo, float hi) { unsigned r; asm volatile("v_cvt_pk_bf16_f32 %0, %1, %2" : "=v"(r) : "v"(lo), "v"(hi)); return r; }
; #define Q_LOAD(j) do { const size_t r = (size_t)(rfirst + rstep * ((j) * 128 + wid * 16 + li)); \
;           _Pragma("unroll") for (int ks = 0; ks < 4; ++ks) qf[ks] = *(const bf16x8*)(Q0 + r * 512 + h * 128 + ks * 32 + kq * 8); } while (0)
; template <int SPLIT> __device__ __forceinline__ void scan_item(const Params& p, unsigned char* smem, const int item, const int vh) {
;     ...
;             mm16<NBV>(acc2, CS + vh * 16384, qf, lane);
;             __builtin_amdgcn_sched_barrier(0);
;             Q_LOAD(jn);
; #pragma unroll
;             for (int nb = 0; nb < NBV; ++nb) acc2[nb] *= exl;
;             __builtin_amdgcn_sched_barrier(0);
;             { bf16x8 pf[4]; ldfrag(pf, KP, wid, lane); mm16<NBV>(acc2, VT + vh * 16384, pf, lane); }
;             __builtin_amdgcn_sched_barrier(0);
;             { bf16_t* hp = P0 + rowl * LDP + dir * 512 + h * 128 + vh * 64 + kq * 4;
; #pragma unroll
;               for (int nb = 0; nb < NBV; ++nb) { u32x2 o; o.x = cvt_pk(acc2[nb][0] * hinv, acc2[nb][1] * hinv); o.y = cvt_pk(acc2[nb][2] * hinv, acc2[nb][3] * hinv);
;                   *(u32x2*)(hp + nb * 16) = o; } }
;             __builtin_amdgcn_sched_barrier(0);
;             float nnew;
;             { bf16x8 vf[4]; ldfrag(vf, VT, vblk, lane);
; #pragma unroll
;               for (int nb = 0; nb < NBV; ++nb) Cacc[nb] *= decay;
;               mm16<NBV>(Cacc, KT + kh * 16384, vf, lane);
	v_mfma_f32_16x16x32_bf16 v[156:159], v[24:27], v[12:15], v[20:23]
	s_nop 0
	v_add_u32_e32 v12, s0, v96
	v_mul_lo_u32 v12, v12, s3
	v_add_u32_e32 v12, s33, v12
	v_ashrrev_i32_e32 v13, 31, v12
	v_lshlrev_b64 v[12:13], 10, v[12:13]
	v_lshl_add_u64 v[12:13], v[76:77], 0, v[12:13]
	global_load_dwordx4 v[28:31], v[12:13], off
	global_load_dwordx4 v[24:27], v[12:13], off offset:64
	global_load_dwordx4 v[20:23], v[12:13], off offset:128
	s_nop 0
	global_load_dwordx4 v[12:15], v[12:13], off offset:192
	v_pk_mul_f32 v[154:155], v[86:87], v[154:155] op_sel_hi:[0,1]
	v_pk_mul_f32 v[152:153], v[86:87], v[152:153] op_sel_hi:[0,1]
	v_pk_mul_f32 v[90:91], v[86:87], v[90:91] op_sel_hi:[0,1]
	v_pk_mul_f32 v[88:89], v[86:87], v[88:89] op_sel_hi:[0,1]
	v_pk_mul_f32 v[94:95], v[86:87], v[94:95] op_sel_hi:[0,1]
	v_rcp_f32_e32 v151, v151
	v_pk_mul_f32 v[92:93], v[86:87], v[92:93] op_sel_hi:[0,1]
	v_pk_mul_f32 v[158:159], v[86:87], v[158:159] op_sel_hi:[0,1]
	v_pk_mul_f32 v[156:157], v[86:87], v[156:157] op_sel_hi:[0,1]
	v_add_u32_e32 v86, s90, v107
	ds_read_b128 v[160:163], v86 offset:32768
	v_add_u32_e32 v164, v115, v114
	ds_read_b128 v[164:167], v164
	ds_read_b128 v[172:175], v86 offset:36864
	v_add_u32_e32 v168, v116, v114
	ds_read_b128 v[178:181], v168
	s_waitcnt lgkmcnt(1)
	v_mfma_f32_16x16x32_bf16 v[88:91], v[172:175], v[164:167], v[88:91]
	v_add_u32_e32 v168, v118, v114
	ds_read_b128 v[172:175], v86 offset:45056
	v_mfma_f32_16x16x32_bf16 v[152:155], v[160:163], v[164:167], v[152:155]
	ds_read_b128 v[160:163], v86 offset:40960
	v_add_u32_e32 v86, v117, v114
	s_waitcnt lgkmcnt(0)
	v_mfma_f32_16x16x32_bf16 v[92:95], v[160:163], v[164:167], v[92:95]
	ds_read_b128 v[160:163], v86
	ds_read_b128 v[182:185], v168
	v_mfma_f32_16x16x32_bf16 v[156:159], v[172:175], v[164:167], v[156:159]
	v_add_u32_e32 v86, s90, v109
	ds_read_b128 v[226:229], v86 offset:32768
	ds_read_b128 v[230:233], v86 offset:36864
	ds_read_b128 v[234:237], v86 offset:40960
	ds_read_b128 v[164:167], v86 offset:45056
	s_waitcnt lgkmcnt(3)
	v_mfma_f32_16x16x32_bf16 v[152:155], v[226:229], v[178:181], v[152:155]
	s_nop 0
	s_waitcnt lgkmcnt(2)
	v_mfma_f32_16x16x32_bf16 v[88:91], v[230:233], v[178:181], v[88:91]
	s_nop 0
	s_waitcnt lgkmcnt(1)
	v_mfma_f32_16x16x32_bf16 v[92:95], v[234:237], v[178:181], v[92:95]
	s_nop 0
	s_waitcnt lgkmcnt(0)
	v_mfma_f32_16x16x32_bf16 v[156:159], v[164:167], v[178:181], v[156:159]
	s_nop 0
	v_add_u32_e32 v86, s90, v111
	ds_read_b128 v[226:229], v86 offset:32768
	ds_read_b128 v[230:233], v86 offset:36864
	ds_read_b128 v[234:237], v86 offset:40960
	ds_read_b128 v[164:167], v86 offset:45056
	s_waitcnt lgkmcnt(3)
	v_mfma_f32_16x16x32_bf16 v[152:155], v[226:229], v[160:163], v[152:155]
	s_nop 0
	s_waitcnt lgkmcnt(2)
	v_mfma_f32_16x16x32_bf16 v[88:91], v[230:233], v[160:163], v[88:91]
	s_nop 0
	s_waitcnt lgkmcnt(1)
	v_mfma_f32_16x16x32_bf16 v[92:95], v[234:237], v[160:163], v[92:95]
	s_nop 0
	s_waitcnt lgkmcnt(0)
	v_mfma_f32_16x16x32_bf16 v[156:159], v[164:167], v[160:163], v[156:159]
	s_nop 0
	v_add_u32_e32 v86, s90, v113
	ds_read_b128 v[226:229], v86 offset:32768
	ds_read_b128 v[230:233], v86 offset:36864
	ds_read_b128 v[234:237], v86 offset:40960
	ds_read_b128 v[160:163], v86 offset:45056
	s_waitcnt lgkmcnt(3)
	v_mfma_f32_16x16x32_bf16 v[152:155], v[226:229], v[182:185], v[152:155]
	s_nop 0
	s_waitcnt lgkmcnt(2)
	v_mfma_f32_16x16x32_bf16 v[88:91], v[230:233], v[182:185], v[88:91]
	s_nop 0
	s_waitcnt lgkmcnt(1)
	v_mfma_f32_16x16x32_bf16 v[92:95], v[234:237], v[182:185], v[92:95]
	s_nop 0
	s_waitcnt lgkmcnt(0)
	v_mfma_f32_16x16x32_bf16 v[156:159], v[160:163], v[182:185], v[156:159]
	s_nop 0
	v_mul_f32_e32 v86, v151, v152
	v_mul_f32_e32 v152, v151, v153
	v_cvt_pk_bf16_f32 v152, v86, v152
	v_mul_f32_e32 v86, v151, v154
	v_mul_f32_e32 v153, v151, v155
	v_mad_i64_i32 v[160:161], s[4:5], v131, s88, v[78:79]
	v_cvt_pk_bf16_f32 v153, v86, v153
	v_mul_f32_e32 v86, v151, v88
	v_mul_f32_e32 v88, v151, v89
	global_store_dwordx2 v[160:161], v[152:153], off
	v_cvt_pk_bf16_f32 v88, v86, v88
	v_mul_f32_e32 v86, v151, v90
	v_mul_f32_e32 v89, v151, v91
	v_cvt_pk_bf16_f32 v89, v86, v89
	global_store_dwordx2 v[160:161], v[88:89], off offset:32
	v_mul_f32_e32 v86, v151, v92
	v_mul_f32_e32 v88, v151, v93
	v_cvt_pk_bf16_f32 v88, v86, v88
	v_mul_f32_e32 v86, v151, v94
	v_mul_f32_e32 v89, v151, v95
	v_cvt_pk_bf16_f32 v89, v86, v89
	global_store_dwordx2 v[160:161], v[88:89], off offset:64
	v_mul_f32_e32 v86, v151, v156
	v_mul_f32_e32 v88, v151, v157
	v_cvt_pk_bf16_f32 v88, v86, v88
	v_mul_f32_e32 v86, v151, v158
	v_mul_f32_e32 v89, v151, v159
	v_cvt_pk_bf16_f32 v89, v86, v89
	global_store_dwordx2 v[160:161], v[88:89], off offset:96
	v_add_u32_e32 v86, v120, v107
	ds_read_b128 v[88:91], v86
	v_add_u32_e32 v92, v115, v119
	ds_read_b128 v[92:95], v92 offset:32768
	ds_read_b128 v[152:155], v86 offset:4096
	v_add_u32_e32 v151, v116, v119
	v_pk_mul_f32 v[50:51], v[50:51], v[84:85] op_sel_hi:[1,0]
	v_pk_mul_f32 v[48:49], v[48:49], v[84:85] op_sel_hi:[1,0]
	ds_read_b128 v[156:159], v151 offset:32768
	ds_read_b128 v[160:163], v86 offset:8192
	v_add_u32_e32 v151, v117, v119
	v_pk_mul_f32 v[54:55], v[54:55], v[84:85] op_sel_hi:[1,0]
	s_waitcnt lgkmcnt(3)
	v_mfma_f32_16x16x32_bf16 v[48:51], v[88:91], v[92:95], v[48:51]
	ds_read_b128 v[88:91], v86 offset:12288
	v_pk_mul_f32 v[52:53], v[52:53], v[84:85] op_sel_hi:[1,0]
	v_pk_mul_f32 v[58:59], v[58:59], v[84:85] op_sel_hi:[1,0]
	v_pk_mul_f32 v[56:57], v[56:57], v[84:85] op_sel_hi:[1,0]
	s_waitcnt lgkmcnt(3)
; __device__ __forceinline__ unsigned cvt_pk(float lo, float hi) { unsigned r; asm volatile("v_cvt_pk_bf16_f32 %0, %1, %2" : "=v"(r) : "v"(lo), "v"(hi)); return r; }
; __device__ __forceinline__ float bflo(unsigned w) { return __uint_as_float(w << 16); }
; __device__ __forceinline__ float bfhi(unsigned w) { return __uint_as_float(w & 0xffff0000u); }
; template <int SPLIT> __device__ __forceinline__ void scan_item(const Params& p, unsigned char* smem, const int item, const int vh) {
;     ...
;             { bf16x8 vf[4]; ldfrag(vf, VT, vblk, lane);
; #pragma unroll
;               for (int nb = 0; nb < NBV; ++nb) Cacc[nb] *= decay;
;               mm16<NBV>(Cacc, KT + kh * 16384, vf, lane);
;               float part = 0.f;
; #pragma unroll
;               for (int ks = 0; ks < 4; ++ks) { const u32x4 kw = *(const u32x4*)(KT + swz(wid * 16 + li, ks * 4 + kq));
;                   part += bflo(kw.x) + bfhi(kw.x) + bflo(kw.y) + bfhi(kw.y) + bflo(kw.z) + bfhi(kw.z) + bflo(kw.w) + bfhi(kw.w); }
;               part += __shfl_xor(part, 16); part += __shfl_xor(part, 32);
;               nnew = decay * n_s[wid * 16 + li] + part; }
;             __syncthreads();
; #pragma unroll
;             for (int nb = 0; nb < NBV; ++nb) { u32x2 o; o.x = cvt_pk(Cacc[nb][0], Cacc[nb][1]); o.y = cvt_pk(Cacc[nb][2], Cacc[nb][3]);
;                 *(u32x2*)(CS + swz(vblk * 16 + li, (kh * 4 + nb) * 2 + (kq >> 1)) + (kq & 1) * 8) = o; }
;             if (kq == 0) n_s[wid * 16 + li] = nnew;
	v_mfma_f32_16x16x32_bf16 v[52:55], v[152:155], v[92:95], v[52:55]
	v_add_u32_e32 v86, v118, v119
	v_pk_mul_f32 v[62:63], v[62:63], v[84:85] op_sel_hi:[1,0]
	v_pk_mul_f32 v[60:61], v[60:61], v[84:85] op_sel_hi:[1,0]
	s_waitcnt lgkmcnt(1)
	v_mfma_f32_16x16x32_bf16 v[56:59], v[160:163], v[92:95], v[56:59]
	ds_read_b128 v[152:155], v151 offset:32768
	ds_read_b128 v[160:163], v86 offset:32768
	s_waitcnt lgkmcnt(2)
	v_mfma_f32_16x16x32_bf16 v[60:63], v[88:91], v[92:95], v[60:63]
	v_add_u32_e32 v86, v120, v109
	ds_read_b128 v[226:229], v86
	ds_read_b128 v[230:233], v86 offset:4096
	ds_read_b128 v[234:237], v86 offset:8192
	ds_read_b128 v[88:91], v86 offset:12288
	s_waitcnt lgkmcnt(3)
	v_mfma_f32_16x16x32_bf16 v[48:51], v[226:229], v[156:159], v[48:51]
	s_nop 0
	s_waitcnt lgkmcnt(2)
	v_mfma_f32_16x16x32_bf16 v[52:55], v[230:233], v[156:159], v[52:55]
	s_nop 0
	s_waitcnt lgkmcnt(1)
	v_mfma_f32_16x16x32_bf16 v[56:59], v[234:237], v[156:159], v[56:59]
	s_nop 0
	s_waitcnt lgkmcnt(0)
	v_mfma_f32_16x16x32_bf16 v[60:63], v[88:91], v[156:159], v[60:63]
	s_nop 0
	v_add_u32_e32 v86, v120, v111
	ds_read_b128 v[226:229], v86
	ds_read_b128 v[230:233], v86 offset:4096
	ds_read_b128 v[234:237], v86 offset:8192
	ds_read_b128 v[88:91], v86 offset:12288
	s_waitcnt lgkmcnt(3)
	v_mfma_f32_16x16x32_bf16 v[48:51], v[226:229], v[152:155], v[48:51]
	s_nop 0
	s_waitcnt lgkmcnt(2)
	v_mfma_f32_16x16x32_bf16 v[52:55], v[230:233], v[152:155], v[52:55]
	s_nop 0
	s_waitcnt lgkmcnt(1)
	v_mfma_f32_16x16x32_bf16 v[56:59], v[234:237], v[152:155], v[56:59]
	s_nop 0
	s_waitcnt lgkmcnt(0)
	v_mfma_f32_16x16x32_bf16 v[60:63], v[88:91], v[152:155], v[60:63]
	s_nop 0
	v_add_u32_e32 v86, v120, v113
	ds_read_b128 v[226:229], v86
	ds_read_b128 v[230:233], v86 offset:4096
	ds_read_b128 v[234:237], v86 offset:8192
	ds_read_b128 v[88:91], v86 offset:12288
	s_waitcnt lgkmcnt(3)
	v_mfma_f32_16x16x32_bf16 v[48:51], v[226:229], v[160:163], v[48:51]
	s_nop 0
	s_waitcnt lgkmcnt(2)
	v_mfma_f32_16x16x32_bf16 v[52:55], v[230:233], v[160:163], v[52:55]
	s_nop 0
	s_waitcnt lgkmcnt(1)
	v_mfma_f32_16x16x32_bf16 v[56:59], v[234:237], v[160:163], v[56:59]
	s_nop 0
	s_waitcnt lgkmcnt(0)
	v_mfma_f32_16x16x32_bf16 v[60:63], v[88:91], v[160:163], v[60:63]
	s_nop 0
	v_add_u32_e32 v86, v121, v106
	ds_read_b128 v[88:91], v86
	s_waitcnt lgkmcnt(0)
	v_lshlrev_b32_e32 v86, 16, v88
	v_and_b32_e32 v88, 0xffff0000, v88
	v_add_f32_e32 v86, v86, v88
	v_lshlrev_b32_e32 v88, 16, v89
	v_add_f32_e32 v86, v86, v88
	v_and_b32_e32 v88, 0xffff0000, v89
	v_add_f32_e32 v86, v86, v88
	v_lshlrev_b32_e32 v88, 16, v90
	v_add_f32_e32 v86, v86, v88
	v_and_b32_e32 v88, 0xffff0000, v90
	v_add_f32_e32 v86, v86, v88
	v_lshlrev_b32_e32 v88, 16, v91
	v_add_f32_e32 v86, v86, v88
	v_and_b32_e32 v88, 0xffff0000, v91
	v_add_f32_e32 v86, v86, v88
	v_add_u32_e32 v88, v121, v108
	ds_read_b128 v[88:91], v88
	v_add_f32_e32 v86, 0, v86
	s_waitcnt lgkmcnt(0)
	v_lshlrev_b32_e32 v92, 16, v88
	v_and_b32_e32 v88, 0xffff0000, v88
	v_add_f32_e32 v88, v92, v88
	v_lshlrev_b32_e32 v92, 16, v89
	v_add_f32_e32 v88, v88, v92
	v_and_b32_e32 v89, 0xffff0000, v89
	v_add_f32_e32 v88, v88, v89
	v_lshlrev_b32_e32 v89, 16, v90
	v_add_f32_e32 v88, v88, v89
	v_and_b32_e32 v89, 0xffff0000, v90
	v_add_f32_e32 v88, v88, v89
	v_lshlrev_b32_e32 v89, 16, v91
	v_add_f32_e32 v88, v88, v89
	v_and_b32_e32 v89, 0xffff0000, v91
	v_add_f32_e32 v88, v88, v89
	v_add_f32_e32 v86, v86, v88
	v_add_u32_e32 v88, v121, v110
	ds_read_b128 v[88:91], v88
	s_waitcnt lgkmcnt(0)
	v_lshlrev_b32_e32 v92, 16, v88
	v_and_b32_e32 v88, 0xffff0000, v88
	v_add_f32_e32 v88, v92, v88
	v_lshlrev_b32_e32 v92, 16, v89
	v_add_f32_e32 v88, v88, v92
	v_and_b32_e32 v89, 0xffff0000, v89
	v_add_f32_e32 v88, v88, v89
	v_lshlrev_b32_e32 v89, 16, v90
	v_add_f32_e32 v88, v88, v89
	v_and_b32_e32 v89, 0xffff0000, v90
	v_add_f32_e32 v88, v88, v89
	v_lshlrev_b32_e32 v89, 16, v91
	v_add_f32_e32 v88, v88, v89
	v_and_b32_e32 v89, 0xffff0000, v91
	v_add_f32_e32 v88, v88, v89
	v_add_f32_e32 v86, v86, v88
	v_add_u32_e32 v88, v121, v112
	ds_read_b128 v[88:91], v88
	s_waitcnt lgkmcnt(0)
	v_lshlrev_b32_e32 v92, 16, v88
	v_and_b32_e32 v88, 0xffff0000, v88
	v_add_f32_e32 v88, v92, v88
	v_lshlrev_b32_e32 v92, 16, v89
	v_add_f32_e32 v88, v88, v92
	v_and_b32_e32 v89, 0xffff0000, v89
	v_add_f32_e32 v88, v88, v89
	v_lshlrev_b32_e32 v89, 16, v90
	v_add_f32_e32 v88, v88, v89
	v_and_b32_e32 v89, 0xffff0000, v90
	v_add_f32_e32 v88, v88, v89
	v_lshlrev_b32_e32 v89, 16, v91
	v_add_f32_e32 v88, v88, v89
	v_and_b32_e32 v89, 0xffff0000, v91
	v_add_f32_e32 v88, v88, v89
	v_add_f32_e32 v86, v86, v88
	ds_bpermute_b32 v87, v87, v86
	s_waitcnt lgkmcnt(0)
	v_add_f32_e32 v86, v86, v87
	ds_bpermute_b32 v67, v67, v86
	ds_read_b32 v87, v122
	s_waitcnt lgkmcnt(0)
	s_barrier
	v_cvt_pk_bf16_f32 v88, v48, v49
	v_cvt_pk_bf16_f32 v89, v50, v51
	ds_write_b64 v146, v[88:89]
	v_cvt_pk_bf16_f32 v88, v52, v53
	v_cvt_pk_bf16_f32 v89, v54, v55
	ds_write_b64 v147, v[88:89]
	v_cvt_pk_bf16_f32 v88, v56, v57
	v_cvt_pk_bf16_f32 v89, v58, v59
	ds_write_b64 v148, v[88:89]
	v_cvt_pk_bf16_f32 v88, v60, v61
	v_cvt_pk_bf16_f32 v89, v62, v63
	ds_write_b64 v149, v[88:89]
	s_and_saveexec_b64 s[86:87], s[8:9]
	s_cbranch_execz .LBB0_311
	v_add_f32_e32 v67, v86, v67
	v_fmac_f32_e32 v67, v84, v87
	ds_write_b32 v122, v67
	s_branch .LBB0_311
